# speedup vs baseline: 1.0095x; 1.0095x over previous
; __device__ __forceinline__ float sigm_f(float x) { return __builtin_amdgcn_rcpf(1.f + __builtin_amdgcn_exp2f(x * -1.4426950408889634f)); }
; __device__ __forceinline__ float silu_f(float x) { return x * sigm_f(x); }
; #define SCHED __builtin_amdgcn_sched_barrier(0)
; template <int ACT>
; __device__ __forceinline__ void epi_tok(f32x4 (&acc)[2][2][4][2], bf16* __restrict__ dst, int ld, int tok0, int colbase,
;                                         const float* __restrict__ bias, float scale) {
;   TC t = get_tc();
;   const int odd = t.fq & 1;
;   const int paddr = ((t.fq ^ 1) * 16 + t.fr) << 2;
;   _Pragma("unroll") for (int ai = 0; ai < 2; ++ai) _Pragma("unroll") for (int bj = 0; bj < 2; ++bj) _Pragma("unroll") for (int m = 0; m < 4; ++m) {
;     uint2 pk[2];
;     _Pragma("unroll") for (int n = 0; n < 2; ++n) {
;       f32x4 v = acc[ai][bj][m][n];
;       if (ACT == 0) { _Pragma("unroll") for (int j = 0; j < 4; ++j) v[j] = silu_f(v[j]); }
;       else if (ACT == 1) { float4 b = *(const float4*)(bias + colbase + bj * 128 + t.wc * 32 + n * 16 + t.fq * 4);
;         v[0] = sigm_f(v[0] + b.x); v[1] = sigm_f(v[1] + b.y); v[2] = sigm_f(v[2] + b.z); v[3] = sigm_f(v[3] + b.w); }
;       else { _Pragma("unroll") for (int j = 0; j < 4; ++j) v[j] *= scale; }
;       pk[n] = pack4(v[0], v[1], v[2], v[3]);
;     }
;     const uint2 snd = odd ? pk[0] : pk[1];
;     uint2 rcv;
;     rcv.x = (unsigned)__builtin_amdgcn_ds_bpermute(paddr, (int)snd.x);
;     rcv.y = (unsigned)__builtin_amdgcn_ds_bpermute(paddr, (int)snd.y);
;     const u32x4 outv = odd ? u32x4{rcv.x, rcv.y, pk[1].x, pk[1].y} : u32x4{pk[0].x, pk[0].y, rcv.x, rcv.y};
;     const int row = ai * 128 + t.wr * 64 + m * 16 + t.fr;
;     const int col = bj * 128 + t.wc * 32 + (odd ? 16 + (t.fq - 1) * 4 : t.fq * 4);
;     *(u32x4*)(dst + (size_t)(tok0 + row) * ld + colbase + col) = outv;
;     SCHED;
;   }
; }
; __device__ __forceinline__ void phase_inproj(const Params& p, const Grp& g, int l) {
;     ...
;       bf16* dst = (ci < 2) ? SZF : SZA;
;       const int ld = (ci < 2) ? 512 : 1024, colbase = (ci < 2) ? ci * 256 : (ci - 2) * 256;
;       epi_tok<0>(acc, dst, ld, tok0, colbase, nullptr, 1.f);
.LBB0_508:
	s_andn2_b64 s[100:101], exec, s[0:1]
	s_lshl_b32 s98, s6, 11
	s_add_i32 s99, s40, -2
	s_lshl_b32 s99, s99, 17
	s_add_i32 s98, s98, s99
	s_add_i32 s98, s98, 0x23260000
	s_add_u32 s98, s58, s98
	s_addc_u32 s99, s59, 0
	v_lshlrev_b32_e32 v250, 4, v190
	s_and_b64 s[8:9], s[0:1], exec
	s_mov_b32 s7, 0x13260000
	s_cselect_b32 s7, s7, 0x23260000
	s_add_u32 s10, s58, s7
	v_mov_b32_e32 v128, v190
	s_addc_u32 s11, s59, 0
	s_lshl_b32 s7, s40, 8
	s_add_i32 s12, s7, 0xfffffe00
	v_lshlrev_b32_e32 v129, 2, v128
	v_lshrrev_b32_e32 v133, 2, v128
	v_bitop3_b32 v130, v129, 64, v194 bitop3:0x6c
	v_and_b32_e32 v129, 16, v128
	v_ashrrev_i32_e32 v131, 2, v128
	v_and_b32_e32 v133, 12, v133
	s_and_b64 s[8:9], s[0:1], exec
	v_and_b32_e32 v131, 0xffffffc0, v131
	v_lshrrev_b32_e32 v132, 1, v128
	v_add_u32_e32 v134, 12, v133
	v_cmp_eq_u32_e32 vcc, 0, v129
	v_and_or_b32 v128, v128, 15, s6
	s_cselect_b32 s8, s7, s12
	v_cndmask_b32_e32 v129, v134, v133, vcc
	s_mov_b64 vcc, s[100:101]
	s_movk_i32 s7, 0x60
	v_add_u32_e32 v128, v128, v131
	v_mul_f32_e32 v131, 0xbfb8aa3b, v124
	v_and_or_b32 v129, v132, s7, v129
	v_exp_f32_e32 v131, v131
	v_mul_f32_e32 v132, 0xbfb8aa3b, v125
	v_exp_f32_e32 v133, v132
	v_mul_f32_e32 v134, 0xbfb8aa3b, v127
	v_add_f32_e32 v131, 1.0, v131
	v_rcp_f32_e32 v132, v131
	v_add_f32_e32 v131, 1.0, v133
	v_rcp_f32_e32 v133, v131
	v_mul_f32_e32 v131, 0xbfb8aa3b, v126
	v_exp_f32_e32 v131, v131
	v_exp_f32_e32 v134, v134
	v_pk_mul_f32 v[124:125], v[124:125], v[132:133]
	s_ashr_i32 s9, s8, 31
	v_add_f32_e32 v131, 1.0, v131
	v_rcp_f32_e32 v132, v131
	v_add_f32_e32 v131, 1.0, v134
	v_rcp_f32_e32 v133, v131
	v_mul_f32_e32 v131, 0xbfb8aa3b, v120
	v_exp_f32_e32 v131, v131
	v_mul_f32_e32 v134, 0xbfb8aa3b, v121
	v_exp_f32_e32 v134, v134
	v_pk_mul_f32 v[126:127], v[126:127], v[132:133]
	v_add_f32_e32 v131, 1.0, v131
	v_mul_f32_e32 v133, 0xbfb8aa3b, v122
	v_rcp_f32_e32 v132, v131
	v_add_f32_e32 v131, 1.0, v134
	v_exp_f32_e32 v134, v133
	v_mul_f32_e32 v133, 0xbfb8aa3b, v123
	v_exp_f32_e32 v135, v133
	v_rcp_f32_e32 v133, v131
	v_add_f32_e32 v131, 1.0, v134
	v_rcp_f32_e32 v134, v131
	v_add_f32_e32 v131, 1.0, v135
	v_rcp_f32_e32 v135, v131
	v_cvt_pk_bf16_f32 v124, v124, v125
	v_cvt_pk_bf16_f32 v125, v126, v127
	v_pk_mul_f32 v[120:121], v[120:121], v[132:133]
	v_pk_mul_f32 v[122:123], v[122:123], v[134:135]
	v_cvt_pk_bf16_f32 v126, v120, v121
	v_cvt_pk_bf16_f32 v122, v122, v123
	s_lshl_b64 s[6:7], s[8:9], 1
	s_add_u32 s6, s10, s6
	s_addc_u32 s7, s11, s7
	s_and_b64 s[0:1], s[0:1], exec
	v_lshlrev_b32_e32 v186, 1, v129
	v_ashrrev_i32_e32 v129, 31, v128
	s_cselect_b32 s0, 9, 10
	v_lshl_add_u64 v[120:121], s[6:7], 0, v[186:187]
	s_waitcnt lgkmcnt(0)
	s_cbranch_vccnz .Lbfrag_p0
	s_nop 1
	v_permlane16_swap_b32 v125, v122
	v_permlane16_swap_b32 v124, v126
.Lbfrag_p0:
	v_mov_b32_e32 v127, v122
	v_lshlrev_b64 v[122:123], s0, v[128:129]
	v_lshl_add_u64 v[122:123], v[122:123], 1, v[120:121]
	s_cbranch_vccnz .Lbfrag_s0
	global_store_dwordx4 v[122:123], v[124:127], off
	s_branch .Lbfrag_d0
.Lbfrag_s0:
	global_store_dwordx4 v250, v[124:127], s[98:99]
.Lbfrag_d0:
	v_add_u32_e32 v250, 0x2000, v250
	s_nop 1
	v_mul_f32_e32 v124, 0xbfb8aa3b, v116
	v_mul_f32_e32 v125, 0xbfb8aa3b, v117
	v_exp_f32_e32 v124, v124
	v_exp_f32_e32 v125, v125
	v_add_f32_e32 v124, 1.0, v124
	v_add_f32_e32 v125, 1.0, v125
	v_rcp_f32_e32 v124, v124
	v_rcp_f32_e32 v125, v125
	s_nop 0
	v_pk_mul_f32 v[116:117], v[116:117], v[124:125]
	v_mul_f32_e32 v124, 0xbfb8aa3b, v118
	v_mul_f32_e32 v125, 0xbfb8aa3b, v119
	v_exp_f32_e32 v124, v124
	v_exp_f32_e32 v125, v125
	v_add_f32_e32 v124, 1.0, v124
	v_add_f32_e32 v125, 1.0, v125
	v_rcp_f32_e32 v124, v124
	v_rcp_f32_e32 v125, v125
	s_nop 0
	v_pk_mul_f32 v[118:119], v[118:119], v[124:125]
	v_cvt_pk_bf16_f32 v124, v116, v117
	v_mul_f32_e32 v116, 0xbfb8aa3b, v112
	v_mul_f32_e32 v117, 0xbfb8aa3b, v113
	v_exp_f32_e32 v116, v116
	v_exp_f32_e32 v117, v117
	v_cvt_pk_bf16_f32 v118, v118, v119
	v_add_f32_e32 v116, 1.0, v116
	v_add_f32_e32 v117, 1.0, v117
	v_rcp_f32_e32 v116, v116
	v_rcp_f32_e32 v117, v117
	s_nop 0
	v_pk_mul_f32 v[112:113], v[112:113], v[116:117]
	v_mul_f32_e32 v116, 0xbfb8aa3b, v114
	v_mul_f32_e32 v117, 0xbfb8aa3b, v115
	v_exp_f32_e32 v116, v116
	v_exp_f32_e32 v117, v117
	v_cvt_pk_bf16_f32 v112, v112, v113
	v_add_f32_e32 v116, 1.0, v116
	v_add_f32_e32 v117, 1.0, v117
	v_rcp_f32_e32 v116, v116
	v_rcp_f32_e32 v117, v117
	s_nop 0
	v_pk_mul_f32 v[114:115], v[114:115], v[116:117]
	s_nop 0
	v_cvt_pk_bf16_f32 v113, v114, v115
	s_waitcnt lgkmcnt(0)
	s_cbranch_vccnz .Lbfrag_p1
	s_nop 1
	v_permlane16_swap_b32 v124, v112
	v_permlane16_swap_b32 v118, v113
.Lbfrag_p1:
	v_mov_b32_e32 v114, v124
	v_mov_b32_e32 v116, v112
	v_mov_b32_e32 v115, v118
	v_mov_b32_e32 v117, v113
	v_or_b32_e32 v112, 16, v128
	v_ashrrev_i32_e32 v113, 31, v112
	v_lshlrev_b64 v[112:113], s0, v[112:113]
	v_lshl_add_u64 v[112:113], v[112:113], 1, v[120:121]
	s_cbranch_vccnz .Lbfrag_s1
	global_store_dwordx4 v[112:113], v[114:117], off
	s_branch .Lbfrag_d1
.Lbfrag_s1:
	global_store_dwordx4 v250, v[114:117], s[98:99]
; __device__ __forceinline__ float sigm_f(float x) { return __builtin_amdgcn_rcpf(1.f + __builtin_amdgcn_exp2f(x * -1.4426950408889634f)); }
; __device__ __forceinline__ float silu_f(float x) { return x * sigm_f(x); }
; #define SCHED __builtin_amdgcn_sched_barrier(0)
; template <int ACT>
; __device__ __forceinline__ void epi_tok(f32x4 (&acc)[2][2][4][2], bf16* __restrict__ dst, int ld, int tok0, int colbase,
;                                         const float* __restrict__ bias, float scale) {
;     ...
;   _Pragma("unroll") for (int ai = 0; ai < 2; ++ai) _Pragma("unroll") for (int bj = 0; bj < 2; ++bj) _Pragma("unroll") for (int m = 0; m < 4; ++m) {
;     uint2 pk[2];
;     _Pragma("unroll") for (int n = 0; n < 2; ++n) {
;       f32x4 v = acc[ai][bj][m][n];
;       if (ACT == 0) { _Pragma("unroll") for (int j = 0; j < 4; ++j) v[j] = silu_f(v[j]); }
;       else if (ACT == 1) { float4 b = *(const float4*)(bias + colbase + bj * 128 + t.wc * 32 + n * 16 + t.fq * 4);
;         v[0] = sigm_f(v[0] + b.x); v[1] = sigm_f(v[1] + b.y); v[2] = sigm_f(v[2] + b.z); v[3] = sigm_f(v[3] + b.w); }
;       else { _Pragma("unroll") for (int j = 0; j < 4; ++j) v[j] *= scale; }
;       pk[n] = pack4(v[0], v[1], v[2], v[3]);
;     }
;     const uint2 snd = odd ? pk[0] : pk[1];
;     uint2 rcv;
;     rcv.x = (unsigned)__builtin_amdgcn_ds_bpermute(paddr, (int)snd.x);
;     rcv.y = (unsigned)__builtin_amdgcn_ds_bpermute(paddr, (int)snd.y);
;     const u32x4 outv = odd ? u32x4{rcv.x, rcv.y, pk[1].x, pk[1].y} : u32x4{pk[0].x, pk[0].y, rcv.x, rcv.y};
;     const int row = ai * 128 + t.wr * 64 + m * 16 + t.fr;
;     const int col = bj * 128 + t.wc * 32 + (odd ? 16 + (t.fq - 1) * 4 : t.fq * 4);
;     *(u32x4*)(dst + (size_t)(tok0 + row) * ld + colbase + col) = outv;
;     SCHED;
;   }
.Lbfrag_d1:
	v_add_u32_e32 v250, 0x2000, v250
	s_nop 1
	v_mul_f32_e32 v114, 0xbfb8aa3b, v108
	v_mul_f32_e32 v115, 0xbfb8aa3b, v109
	v_exp_f32_e32 v114, v114
	v_exp_f32_e32 v115, v115
	v_add_f32_e32 v114, 1.0, v114
	v_add_f32_e32 v115, 1.0, v115
	v_rcp_f32_e32 v114, v114
	v_rcp_f32_e32 v115, v115
	s_nop 0
	v_pk_mul_f32 v[108:109], v[108:109], v[114:115]
	v_mul_f32_e32 v114, 0xbfb8aa3b, v110
	v_mul_f32_e32 v115, 0xbfb8aa3b, v111
	v_exp_f32_e32 v114, v114
	v_exp_f32_e32 v115, v115
	v_add_f32_e32 v114, 1.0, v114
	v_add_f32_e32 v115, 1.0, v115
	v_rcp_f32_e32 v114, v114
	v_rcp_f32_e32 v115, v115
	s_nop 0
	v_pk_mul_f32 v[110:111], v[110:111], v[114:115]
	v_cvt_pk_bf16_f32 v114, v108, v109
	v_mul_f32_e32 v108, 0xbfb8aa3b, v104
	v_mul_f32_e32 v109, 0xbfb8aa3b, v105
	v_exp_f32_e32 v108, v108
	v_exp_f32_e32 v109, v109
	v_cvt_pk_bf16_f32 v110, v110, v111
	v_add_f32_e32 v108, 1.0, v108
	v_add_f32_e32 v109, 1.0, v109
	v_rcp_f32_e32 v108, v108
	v_rcp_f32_e32 v109, v109
	s_nop 0
	v_pk_mul_f32 v[104:105], v[104:105], v[108:109]
	v_mul_f32_e32 v108, 0xbfb8aa3b, v106
	v_mul_f32_e32 v109, 0xbfb8aa3b, v107
	v_exp_f32_e32 v108, v108
	v_exp_f32_e32 v109, v109
	v_cvt_pk_bf16_f32 v104, v104, v105
	v_add_f32_e32 v108, 1.0, v108
	v_add_f32_e32 v109, 1.0, v109
	v_rcp_f32_e32 v108, v108
	v_rcp_f32_e32 v109, v109
	s_nop 0
	v_pk_mul_f32 v[106:107], v[106:107], v[108:109]
	s_nop 0
	v_cvt_pk_bf16_f32 v105, v106, v107
	s_waitcnt lgkmcnt(0)
	s_cbranch_vccnz .Lbfrag_p2
	s_nop 1
	v_permlane16_swap_b32 v114, v104
	v_permlane16_swap_b32 v110, v105
.Lbfrag_p2:
	v_mov_b32_e32 v106, v114
	v_mov_b32_e32 v108, v104
	v_mov_b32_e32 v107, v110
	v_mov_b32_e32 v109, v105
	v_or_b32_e32 v104, 32, v128
	v_ashrrev_i32_e32 v105, 31, v104
	v_lshlrev_b64 v[104:105], s0, v[104:105]
	v_lshl_add_u64 v[104:105], v[104:105], 1, v[120:121]
	s_cbranch_vccnz .Lbfrag_s2
	global_store_dwordx4 v[104:105], v[106:109], off
	s_branch .Lbfrag_d2
.Lbfrag_s2:
	global_store_dwordx4 v250, v[106:109], s[98:99]
.Lbfrag_d2:
	v_add_u32_e32 v250, 0x2000, v250
	s_nop 1
	v_mul_f32_e32 v106, 0xbfb8aa3b, v100
	v_mul_f32_e32 v107, 0xbfb8aa3b, v101
	v_exp_f32_e32 v106, v106
	v_exp_f32_e32 v107, v107
	v_add_f32_e32 v106, 1.0, v106
	v_add_f32_e32 v107, 1.0, v107
	v_rcp_f32_e32 v106, v106
	v_rcp_f32_e32 v107, v107
	s_nop 0
	v_pk_mul_f32 v[100:101], v[100:101], v[106:107]
	v_mul_f32_e32 v106, 0xbfb8aa3b, v102
	v_mul_f32_e32 v107, 0xbfb8aa3b, v103
	v_exp_f32_e32 v106, v106
	v_exp_f32_e32 v107, v107
	v_add_f32_e32 v106, 1.0, v106
	v_add_f32_e32 v107, 1.0, v107
	v_rcp_f32_e32 v106, v106
	v_rcp_f32_e32 v107, v107
	s_nop 0
	v_pk_mul_f32 v[102:103], v[102:103], v[106:107]
	v_cvt_pk_bf16_f32 v106, v100, v101
	v_mul_f32_e32 v100, 0xbfb8aa3b, v96
	v_mul_f32_e32 v101, 0xbfb8aa3b, v97
	v_exp_f32_e32 v100, v100
	v_exp_f32_e32 v101, v101
	v_cvt_pk_bf16_f32 v102, v102, v103
	v_add_f32_e32 v100, 1.0, v100
	v_add_f32_e32 v101, 1.0, v101
	v_rcp_f32_e32 v100, v100
	v_rcp_f32_e32 v101, v101
	s_nop 0
	v_pk_mul_f32 v[96:97], v[96:97], v[100:101]
	v_mul_f32_e32 v100, 0xbfb8aa3b, v98
	v_mul_f32_e32 v101, 0xbfb8aa3b, v99
	v_exp_f32_e32 v100, v100
	v_exp_f32_e32 v101, v101
	v_cvt_pk_bf16_f32 v96, v96, v97
	v_add_f32_e32 v100, 1.0, v100
	v_add_f32_e32 v101, 1.0, v101
	v_rcp_f32_e32 v100, v100
	v_rcp_f32_e32 v101, v101
	s_nop 0
	v_pk_mul_f32 v[98:99], v[98:99], v[100:101]
	s_nop 0
	v_cvt_pk_bf16_f32 v97, v98, v99
	s_waitcnt lgkmcnt(0)
	s_cbranch_vccnz .Lbfrag_p3
	s_nop 1
	v_permlane16_swap_b32 v106, v96
	v_permlane16_swap_b32 v102, v97
.Lbfrag_p3:
	v_mov_b32_e32 v98, v106
	v_mov_b32_e32 v100, v96
	v_mov_b32_e32 v99, v102
	v_mov_b32_e32 v101, v97
	v_or_b32_e32 v96, 48, v128
	v_ashrrev_i32_e32 v97, 31, v96
	v_lshlrev_b64 v[96:97], s0, v[96:97]
	v_lshl_add_u64 v[96:97], v[96:97], 1, v[120:121]
	s_cbranch_vccnz .Lbfrag_s3
	global_store_dwordx4 v[96:97], v[98:101], off
	s_branch .Lbfrag_d3
.Lbfrag_s3:
	global_store_dwordx4 v250, v[98:101], s[98:99]
.Lbfrag_d3:
	v_add_u32_e32 v250, 0x2000, v250
	s_nop 1
	v_mul_f32_e32 v98, 0xbfb8aa3b, v92
	v_mul_f32_e32 v99, 0xbfb8aa3b, v93
	v_exp_f32_e32 v98, v98
	v_exp_f32_e32 v99, v99
	v_add_f32_e32 v98, 1.0, v98
	v_add_f32_e32 v99, 1.0, v99
	v_rcp_f32_e32 v98, v98
	v_rcp_f32_e32 v99, v99
	s_nop 0
	v_pk_mul_f32 v[92:93], v[92:93], v[98:99]
	v_mul_f32_e32 v98, 0xbfb8aa3b, v94
	v_mul_f32_e32 v99, 0xbfb8aa3b, v95
	v_exp_f32_e32 v98, v98
	v_exp_f32_e32 v99, v99
	v_add_f32_e32 v98, 1.0, v98
	v_add_f32_e32 v99, 1.0, v99
	v_rcp_f32_e32 v98, v98
	v_rcp_f32_e32 v99, v99
	s_nop 0
	v_pk_mul_f32 v[94:95], v[94:95], v[98:99]
	v_cvt_pk_bf16_f32 v98, v92, v93
	v_mul_f32_e32 v92, 0xbfb8aa3b, v88
	v_mul_f32_e32 v93, 0xbfb8aa3b, v89
	v_exp_f32_e32 v92, v92
	v_exp_f32_e32 v93, v93
	v_cvt_pk_bf16_f32 v94, v94, v95
	v_add_f32_e32 v92, 1.0, v92
	v_add_f32_e32 v93, 1.0, v93
	v_rcp_f32_e32 v92, v92
	v_rcp_f32_e32 v93, v93
	s_nop 0
	v_pk_mul_f32 v[88:89], v[88:89], v[92:93]
	v_mul_f32_e32 v92, 0xbfb8aa3b, v90
	v_mul_f32_e32 v93, 0xbfb8aa3b, v91
	v_exp_f32_e32 v92, v92
	v_exp_f32_e32 v93, v93
	v_cvt_pk_bf16_f32 v88, v88, v89
	v_add_f32_e32 v92, 1.0, v92
	v_add_f32_e32 v93, 1.0, v93
	v_rcp_f32_e32 v92, v92
	v_rcp_f32_e32 v93, v93
	s_nop 0
	v_pk_mul_f32 v[90:91], v[90:91], v[92:93]
	s_nop 0
	v_cvt_pk_bf16_f32 v89, v90, v91
	s_waitcnt lgkmcnt(0)
	s_cbranch_vccnz .Lbfrag_p4
	s_nop 1
	v_permlane16_swap_b32 v98, v88
	v_permlane16_swap_b32 v94, v89
.Lbfrag_p4:
	v_mov_b32_e32 v90, v88
	v_mov_b32_e32 v88, v98
	v_mov_b32_e32 v91, v89
	v_mov_b32_e32 v89, v94
	s_cbranch_vccnz .Lbfrag_s4
	global_store_dwordx4 v[122:123], v[88:91], off offset:256
	s_branch .Lbfrag_d4
.Lbfrag_s4:
	global_store_dwordx4 v250, v[88:91], s[98:99]
; __device__ __forceinline__ float sigm_f(float x) { return __builtin_amdgcn_rcpf(1.f + __builtin_amdgcn_exp2f(x * -1.4426950408889634f)); }
; __device__ __forceinline__ float silu_f(float x) { return x * sigm_f(x); }
; #define SCHED __builtin_amdgcn_sched_barrier(0)
; template <int ACT>
; __device__ __forceinline__ void epi_tok(f32x4 (&acc)[2][2][4][2], bf16* __restrict__ dst, int ld, int tok0, int colbase,
;                                         const float* __restrict__ bias, float scale) {
;     ...
;   _Pragma("unroll") for (int ai = 0; ai < 2; ++ai) _Pragma("unroll") for (int bj = 0; bj < 2; ++bj) _Pragma("unroll") for (int m = 0; m < 4; ++m) {
;     uint2 pk[2];
;     _Pragma("unroll") for (int n = 0; n < 2; ++n) {
;       f32x4 v = acc[ai][bj][m][n];
;       if (ACT == 0) { _Pragma("unroll") for (int j = 0; j < 4; ++j) v[j] = silu_f(v[j]); }
;       else if (ACT == 1) { float4 b = *(const float4*)(bias + colbase + bj * 128 + t.wc * 32 + n * 16 + t.fq * 4);
;         v[0] = sigm_f(v[0] + b.x); v[1] = sigm_f(v[1] + b.y); v[2] = sigm_f(v[2] + b.z); v[3] = sigm_f(v[3] + b.w); }
;       else { _Pragma("unroll") for (int j = 0; j < 4; ++j) v[j] *= scale; }
;       pk[n] = pack4(v[0], v[1], v[2], v[3]);
;     }
;     const uint2 snd = odd ? pk[0] : pk[1];
;     uint2 rcv;
;     rcv.x = (unsigned)__builtin_amdgcn_ds_bpermute(paddr, (int)snd.x);
;     rcv.y = (unsigned)__builtin_amdgcn_ds_bpermute(paddr, (int)snd.y);
;     const u32x4 outv = odd ? u32x4{rcv.x, rcv.y, pk[1].x, pk[1].y} : u32x4{pk[0].x, pk[0].y, rcv.x, rcv.y};
;     const int row = ai * 128 + t.wr * 64 + m * 16 + t.fr;
;     const int col = bj * 128 + t.wc * 32 + (odd ? 16 + (t.fq - 1) * 4 : t.fq * 4);
;     *(u32x4*)(dst + (size_t)(tok0 + row) * ld + colbase + col) = outv;
;     SCHED;
;   }
.Lbfrag_d4:
	v_add_u32_e32 v250, 0x2000, v250
	s_nop 1
	v_mul_f32_e32 v88, 0xbfb8aa3b, v84
	v_mul_f32_e32 v89, 0xbfb8aa3b, v85
	v_exp_f32_e32 v88, v88
	v_exp_f32_e32 v89, v89
	v_add_f32_e32 v88, 1.0, v88
	v_add_f32_e32 v89, 1.0, v89
	v_rcp_f32_e32 v88, v88
	v_rcp_f32_e32 v89, v89
	s_nop 0
	v_pk_mul_f32 v[84:85], v[84:85], v[88:89]
	v_mul_f32_e32 v88, 0xbfb8aa3b, v86
	v_mul_f32_e32 v89, 0xbfb8aa3b, v87
	v_exp_f32_e32 v88, v88
	v_exp_f32_e32 v89, v89
	v_add_f32_e32 v88, 1.0, v88
	v_add_f32_e32 v89, 1.0, v89
	v_rcp_f32_e32 v88, v88
	v_rcp_f32_e32 v89, v89
	s_nop 0
	v_pk_mul_f32 v[86:87], v[86:87], v[88:89]
	v_cvt_pk_bf16_f32 v88, v84, v85
	v_mul_f32_e32 v84, 0xbfb8aa3b, v80
	v_mul_f32_e32 v85, 0xbfb8aa3b, v81
	v_exp_f32_e32 v84, v84
	v_exp_f32_e32 v85, v85
	v_cvt_pk_bf16_f32 v86, v86, v87
	v_add_f32_e32 v84, 1.0, v84
	v_add_f32_e32 v85, 1.0, v85
	v_rcp_f32_e32 v84, v84
	v_rcp_f32_e32 v85, v85
	s_nop 0
	v_pk_mul_f32 v[80:81], v[80:81], v[84:85]
	v_mul_f32_e32 v84, 0xbfb8aa3b, v82
	v_mul_f32_e32 v85, 0xbfb8aa3b, v83
	v_exp_f32_e32 v84, v84
	v_exp_f32_e32 v85, v85
	v_cvt_pk_bf16_f32 v80, v80, v81
	v_add_f32_e32 v84, 1.0, v84
	v_add_f32_e32 v85, 1.0, v85
	v_rcp_f32_e32 v84, v84
	v_rcp_f32_e32 v85, v85
	s_nop 0
	v_pk_mul_f32 v[82:83], v[82:83], v[84:85]
	s_nop 0
	v_cvt_pk_bf16_f32 v81, v82, v83
	s_waitcnt lgkmcnt(0)
	s_cbranch_vccnz .Lbfrag_p5
	s_nop 1
	v_permlane16_swap_b32 v88, v80
	v_permlane16_swap_b32 v86, v81
.Lbfrag_p5:
	v_mov_b32_e32 v82, v80
	v_mov_b32_e32 v80, v88
	v_mov_b32_e32 v83, v81
	v_mov_b32_e32 v81, v86
	s_cbranch_vccnz .Lbfrag_s5
	global_store_dwordx4 v[112:113], v[80:83], off offset:256
	s_branch .Lbfrag_d5
.Lbfrag_s5:
	global_store_dwordx4 v250, v[80:83], s[98:99]
.Lbfrag_d5:
	v_add_u32_e32 v250, 0x2000, v250
	s_nop 1
	v_mul_f32_e32 v80, 0xbfb8aa3b, v76
	v_mul_f32_e32 v81, 0xbfb8aa3b, v77
	v_exp_f32_e32 v80, v80
	v_exp_f32_e32 v81, v81
	v_add_f32_e32 v80, 1.0, v80
	v_add_f32_e32 v81, 1.0, v81
	v_rcp_f32_e32 v80, v80
	v_rcp_f32_e32 v81, v81
	s_nop 0
	v_pk_mul_f32 v[76:77], v[76:77], v[80:81]
	v_mul_f32_e32 v80, 0xbfb8aa3b, v78
	v_mul_f32_e32 v81, 0xbfb8aa3b, v79
	v_exp_f32_e32 v80, v80
	v_exp_f32_e32 v81, v81
	v_add_f32_e32 v80, 1.0, v80
	v_add_f32_e32 v81, 1.0, v81
	v_rcp_f32_e32 v80, v80
	v_rcp_f32_e32 v81, v81
	s_nop 0
	v_pk_mul_f32 v[78:79], v[78:79], v[80:81]
	v_cvt_pk_bf16_f32 v80, v76, v77
	v_mul_f32_e32 v76, 0xbfb8aa3b, v72
	v_mul_f32_e32 v77, 0xbfb8aa3b, v73
	v_exp_f32_e32 v76, v76
	v_exp_f32_e32 v77, v77
	v_cvt_pk_bf16_f32 v78, v78, v79
	v_add_f32_e32 v76, 1.0, v76
	v_add_f32_e32 v77, 1.0, v77
	v_rcp_f32_e32 v76, v76
	v_rcp_f32_e32 v77, v77
	s_nop 0
	v_pk_mul_f32 v[72:73], v[72:73], v[76:77]
	v_mul_f32_e32 v76, 0xbfb8aa3b, v74
	v_mul_f32_e32 v77, 0xbfb8aa3b, v75
	v_exp_f32_e32 v76, v76
	v_exp_f32_e32 v77, v77
	v_cvt_pk_bf16_f32 v72, v72, v73
	v_add_f32_e32 v76, 1.0, v76
	v_add_f32_e32 v77, 1.0, v77
	v_rcp_f32_e32 v76, v76
	v_rcp_f32_e32 v77, v77
	s_nop 0
	v_pk_mul_f32 v[74:75], v[74:75], v[76:77]
	s_nop 0
	v_cvt_pk_bf16_f32 v73, v74, v75
	s_waitcnt lgkmcnt(0)
	s_cbranch_vccnz .Lbfrag_p6
	s_nop 1
	v_permlane16_swap_b32 v80, v72
	v_permlane16_swap_b32 v78, v73
.Lbfrag_p6:
	v_mov_b32_e32 v74, v72
	v_mov_b32_e32 v72, v80
	v_mov_b32_e32 v75, v73
	v_mov_b32_e32 v73, v78
	s_cbranch_vccnz .Lbfrag_s6
	global_store_dwordx4 v[104:105], v[72:75], off offset:256
	s_branch .Lbfrag_d6
.Lbfrag_s6:
	global_store_dwordx4 v250, v[72:75], s[98:99]
.Lbfrag_d6:
	v_add_u32_e32 v250, 0x2000, v250
	s_nop 1
	v_mul_f32_e32 v72, 0xbfb8aa3b, v68
	v_mul_f32_e32 v73, 0xbfb8aa3b, v69
	v_exp_f32_e32 v72, v72
	v_exp_f32_e32 v73, v73
	v_add_f32_e32 v72, 1.0, v72
	v_add_f32_e32 v73, 1.0, v73
	v_rcp_f32_e32 v72, v72
	v_rcp_f32_e32 v73, v73
	s_nop 0
	v_pk_mul_f32 v[68:69], v[68:69], v[72:73]
	v_mul_f32_e32 v72, 0xbfb8aa3b, v70
	v_mul_f32_e32 v73, 0xbfb8aa3b, v71
	v_exp_f32_e32 v72, v72
	v_exp_f32_e32 v73, v73
	v_add_f32_e32 v72, 1.0, v72
	v_add_f32_e32 v73, 1.0, v73
	v_rcp_f32_e32 v72, v72
	v_rcp_f32_e32 v73, v73
	s_nop 0
	v_pk_mul_f32 v[70:71], v[70:71], v[72:73]
	v_cvt_pk_bf16_f32 v72, v68, v69
	v_mul_f32_e32 v68, 0xbfb8aa3b, v64
	v_mul_f32_e32 v69, 0xbfb8aa3b, v65
	v_exp_f32_e32 v68, v68
	v_exp_f32_e32 v69, v69
	v_cvt_pk_bf16_f32 v70, v70, v71
	v_add_f32_e32 v68, 1.0, v68
	v_add_f32_e32 v69, 1.0, v69
	v_rcp_f32_e32 v68, v68
	v_rcp_f32_e32 v69, v69
	s_nop 0
	v_pk_mul_f32 v[64:65], v[64:65], v[68:69]
	v_mul_f32_e32 v68, 0xbfb8aa3b, v66
	v_mul_f32_e32 v69, 0xbfb8aa3b, v67
	v_exp_f32_e32 v68, v68
	v_exp_f32_e32 v69, v69
	v_cvt_pk_bf16_f32 v64, v64, v65
	v_add_f32_e32 v68, 1.0, v68
	v_add_f32_e32 v69, 1.0, v69
	v_rcp_f32_e32 v68, v68
	v_rcp_f32_e32 v69, v69
	s_nop 0
	v_pk_mul_f32 v[66:67], v[66:67], v[68:69]
	s_nop 0
	v_cvt_pk_bf16_f32 v65, v66, v67
	s_waitcnt lgkmcnt(0)
	s_cbranch_vccnz .Lbfrag_p7
	s_nop 1
	v_permlane16_swap_b32 v72, v64
	v_permlane16_swap_b32 v70, v65
.Lbfrag_p7:
	v_mov_b32_e32 v66, v64
	v_mov_b32_e32 v64, v72
	v_mov_b32_e32 v67, v65
	v_mov_b32_e32 v65, v70
	s_cbranch_vccnz .Lbfrag_s7
	global_store_dwordx4 v[96:97], v[64:67], off offset:256
	s_branch .Lbfrag_d7
.Lbfrag_s7:
	global_store_dwordx4 v250, v[64:67], s[98:99]
; __device__ __forceinline__ float sigm_f(float x) { return __builtin_amdgcn_rcpf(1.f + __builtin_amdgcn_exp2f(x * -1.4426950408889634f)); }
; __device__ __forceinline__ float silu_f(float x) { return x * sigm_f(x); }
; #define SCHED __builtin_amdgcn_sched_barrier(0)
; template <int ACT>
; __device__ __forceinline__ void epi_tok(f32x4 (&acc)[2][2][4][2], bf16* __restrict__ dst, int ld, int tok0, int colbase,
;                                         const float* __restrict__ bias, float scale) {
;     ...
;   _Pragma("unroll") for (int ai = 0; ai < 2; ++ai) _Pragma("unroll") for (int bj = 0; bj < 2; ++bj) _Pragma("unroll") for (int m = 0; m < 4; ++m) {
;     uint2 pk[2];
;     _Pragma("unroll") for (int n = 0; n < 2; ++n) {
;       f32x4 v = acc[ai][bj][m][n];
;       if (ACT == 0) { _Pragma("unroll") for (int j = 0; j < 4; ++j) v[j] = silu_f(v[j]); }
;       else if (ACT == 1) { float4 b = *(const float4*)(bias + colbase + bj * 128 + t.wc * 32 + n * 16 + t.fq * 4);
;         v[0] = sigm_f(v[0] + b.x); v[1] = sigm_f(v[1] + b.y); v[2] = sigm_f(v[2] + b.z); v[3] = sigm_f(v[3] + b.w); }
;       else { _Pragma("unroll") for (int j = 0; j < 4; ++j) v[j] *= scale; }
;       pk[n] = pack4(v[0], v[1], v[2], v[3]);
;     }
;     const uint2 snd = odd ? pk[0] : pk[1];
;     uint2 rcv;
;     rcv.x = (unsigned)__builtin_amdgcn_ds_bpermute(paddr, (int)snd.x);
;     rcv.y = (unsigned)__builtin_amdgcn_ds_bpermute(paddr, (int)snd.y);
;     const u32x4 outv = odd ? u32x4{rcv.x, rcv.y, pk[1].x, pk[1].y} : u32x4{pk[0].x, pk[0].y, rcv.x, rcv.y};
;     const int row = ai * 128 + t.wr * 64 + m * 16 + t.fr;
;     const int col = bj * 128 + t.wc * 32 + (odd ? 16 + (t.fq - 1) * 4 : t.fq * 4);
;     *(u32x4*)(dst + (size_t)(tok0 + row) * ld + colbase + col) = outv;
;     SCHED;
;   }
.Lbfrag_d7:
	v_add_u32_e32 v250, 0x2000, v250
	s_nop 1
	v_mul_f32_e32 v64, 0xbfb8aa3b, v60
	v_mul_f32_e32 v65, 0xbfb8aa3b, v61
	v_exp_f32_e32 v64, v64
	v_exp_f32_e32 v65, v65
	v_mul_f32_e32 v66, 0xbfb8aa3b, v62
	v_mul_f32_e32 v67, 0xbfb8aa3b, v63
	v_add_f32_e32 v64, 1.0, v64
	v_add_f32_e32 v65, 1.0, v65
	v_rcp_f32_e32 v64, v64
	v_rcp_f32_e32 v65, v65
	v_exp_f32_e32 v66, v66
	v_exp_f32_e32 v67, v67
	v_pk_mul_f32 v[60:61], v[60:61], v[64:65]
	v_add_f32_e32 v64, 1.0, v66
	v_add_f32_e32 v65, 1.0, v67
	v_mul_f32_e32 v66, 0xbfb8aa3b, v56
	v_mul_f32_e32 v67, 0xbfb8aa3b, v57
	v_rcp_f32_e32 v64, v64
	v_rcp_f32_e32 v65, v65
	v_exp_f32_e32 v66, v66
	v_exp_f32_e32 v67, v67
	v_cvt_pk_bf16_f32 v68, v60, v61
	v_pk_mul_f32 v[62:63], v[62:63], v[64:65]
	v_add_f32_e32 v64, 1.0, v66
	v_add_f32_e32 v65, 1.0, v67
	v_mul_f32_e32 v66, 0xbfb8aa3b, v58
	v_mul_f32_e32 v67, 0xbfb8aa3b, v59
	v_exp_f32_e32 v66, v66
	v_exp_f32_e32 v67, v67
	v_rcp_f32_e32 v64, v64
	v_rcp_f32_e32 v65, v65
	v_add_f32_e32 v66, 1.0, v66
	v_add_f32_e32 v67, 1.0, v67
	v_rcp_f32_e32 v66, v66
	v_rcp_f32_e32 v67, v67
	v_pk_mul_f32 v[56:57], v[56:57], v[64:65]
	v_cvt_pk_bf16_f32 v62, v62, v63
	v_cvt_pk_bf16_f32 v57, v56, v57
	v_pk_mul_f32 v[58:59], v[58:59], v[66:67]
	v_cvt_pk_bf16_f32 v58, v58, v59
	v_add_u32_e32 v56, 0x80, v128
	s_waitcnt lgkmcnt(0)
	s_cbranch_vccnz .Lbfrag_p8
	s_nop 1
	v_permlane16_swap_b32 v68, v57
	v_permlane16_swap_b32 v62, v58
.Lbfrag_p8:
	v_mov_b32_e32 v60, v57
	v_mov_b32_e32 v59, v62
	v_mov_b32_e32 v61, v58
	v_mov_b32_e32 v58, v68
	v_ashrrev_i32_e32 v57, 31, v56
	v_lshlrev_b64 v[56:57], s0, v[56:57]
	v_lshl_add_u64 v[56:57], v[56:57], 1, v[120:121]
	s_cbranch_vccnz .Lbfrag_s8
	global_store_dwordx4 v[56:57], v[58:61], off
	s_branch .Lbfrag_d8
.Lbfrag_s8:
	global_store_dwordx4 v250, v[58:61], s[98:99]
.Lbfrag_d8:
	v_add_u32_e32 v250, 0x2000, v250
	s_nop 1
	v_mul_f32_e32 v58, 0xbfb8aa3b, v52
	v_mul_f32_e32 v59, 0xbfb8aa3b, v53
	v_exp_f32_e32 v58, v58
	v_exp_f32_e32 v59, v59
	v_add_f32_e32 v58, 1.0, v58
	v_add_f32_e32 v59, 1.0, v59
	v_rcp_f32_e32 v58, v58
	v_rcp_f32_e32 v59, v59
	s_nop 0
	v_pk_mul_f32 v[52:53], v[52:53], v[58:59]
	v_mul_f32_e32 v58, 0xbfb8aa3b, v54
	v_mul_f32_e32 v59, 0xbfb8aa3b, v55
	v_exp_f32_e32 v58, v58
	v_exp_f32_e32 v59, v59
	v_add_f32_e32 v58, 1.0, v58
	v_add_f32_e32 v59, 1.0, v59
	v_rcp_f32_e32 v58, v58
	v_rcp_f32_e32 v59, v59
	s_nop 0
	v_pk_mul_f32 v[54:55], v[54:55], v[58:59]
	v_cvt_pk_bf16_f32 v58, v52, v53
	v_mul_f32_e32 v52, 0xbfb8aa3b, v48
	v_mul_f32_e32 v53, 0xbfb8aa3b, v49
	v_exp_f32_e32 v52, v52
	v_exp_f32_e32 v53, v53
	v_cvt_pk_bf16_f32 v54, v54, v55
	v_add_f32_e32 v52, 1.0, v52
	v_add_f32_e32 v53, 1.0, v53
	v_rcp_f32_e32 v52, v52
	v_rcp_f32_e32 v53, v53
	s_nop 0
	v_pk_mul_f32 v[48:49], v[48:49], v[52:53]
	v_mul_f32_e32 v52, 0xbfb8aa3b, v50
	v_mul_f32_e32 v53, 0xbfb8aa3b, v51
	v_exp_f32_e32 v52, v52
	v_exp_f32_e32 v53, v53
	v_cvt_pk_bf16_f32 v48, v48, v49
	v_add_f32_e32 v52, 1.0, v52
	v_add_f32_e32 v53, 1.0, v53
	v_rcp_f32_e32 v52, v52
	v_rcp_f32_e32 v53, v53
	s_nop 0
	v_pk_mul_f32 v[50:51], v[50:51], v[52:53]
	s_nop 0
	v_cvt_pk_bf16_f32 v49, v50, v51
	s_waitcnt lgkmcnt(0)
	s_cbranch_vccnz .Lbfrag_p9
	s_nop 1
	v_permlane16_swap_b32 v58, v48
	v_permlane16_swap_b32 v54, v49
.Lbfrag_p9:
	v_mov_b32_e32 v50, v58
	v_mov_b32_e32 v52, v48
	v_mov_b32_e32 v51, v54
	v_mov_b32_e32 v53, v49
	v_add_u32_e32 v48, 0x90, v128
	v_ashrrev_i32_e32 v49, 31, v48
	v_lshlrev_b64 v[48:49], s0, v[48:49]
	v_lshl_add_u64 v[48:49], v[48:49], 1, v[120:121]
	s_cbranch_vccnz .Lbfrag_s9
	global_store_dwordx4 v[48:49], v[50:53], off
	s_branch .Lbfrag_d9
.Lbfrag_s9:
	global_store_dwordx4 v250, v[50:53], s[98:99]
.Lbfrag_d9:
	v_add_u32_e32 v250, 0x2000, v250
	s_nop 1
	v_mul_f32_e32 v50, 0xbfb8aa3b, v44
	v_mul_f32_e32 v51, 0xbfb8aa3b, v45
	v_exp_f32_e32 v50, v50
	v_exp_f32_e32 v51, v51
	v_add_f32_e32 v50, 1.0, v50
	v_add_f32_e32 v51, 1.0, v51
	v_rcp_f32_e32 v50, v50
	v_rcp_f32_e32 v51, v51
	s_nop 0
	v_pk_mul_f32 v[44:45], v[44:45], v[50:51]
	v_mul_f32_e32 v50, 0xbfb8aa3b, v46
	v_mul_f32_e32 v51, 0xbfb8aa3b, v47
	v_exp_f32_e32 v50, v50
	v_exp_f32_e32 v51, v51
	v_add_f32_e32 v50, 1.0, v50
	v_add_f32_e32 v51, 1.0, v51
	v_rcp_f32_e32 v50, v50
	v_rcp_f32_e32 v51, v51
	s_nop 0
	v_pk_mul_f32 v[46:47], v[46:47], v[50:51]
	v_cvt_pk_bf16_f32 v50, v44, v45
	v_mul_f32_e32 v44, 0xbfb8aa3b, v40
	v_mul_f32_e32 v45, 0xbfb8aa3b, v41
	v_exp_f32_e32 v44, v44
	v_exp_f32_e32 v45, v45
	v_cvt_pk_bf16_f32 v46, v46, v47
	v_add_f32_e32 v44, 1.0, v44
	v_add_f32_e32 v45, 1.0, v45
	v_rcp_f32_e32 v44, v44
	v_rcp_f32_e32 v45, v45
	s_nop 0
	v_pk_mul_f32 v[40:41], v[40:41], v[44:45]
	v_mul_f32_e32 v44, 0xbfb8aa3b, v42
	v_mul_f32_e32 v45, 0xbfb8aa3b, v43
	v_exp_f32_e32 v44, v44
	v_exp_f32_e32 v45, v45
	v_cvt_pk_bf16_f32 v40, v40, v41
	v_add_f32_e32 v44, 1.0, v44
	v_add_f32_e32 v45, 1.0, v45
	v_rcp_f32_e32 v44, v44
	v_rcp_f32_e32 v45, v45
	s_nop 0
	v_pk_mul_f32 v[42:43], v[42:43], v[44:45]
	s_nop 0
	v_cvt_pk_bf16_f32 v41, v42, v43
	s_waitcnt lgkmcnt(0)
	s_cbranch_vccnz .Lbfrag_p10
	s_nop 1
	v_permlane16_swap_b32 v50, v40
	v_permlane16_swap_b32 v46, v41
.Lbfrag_p10:
	v_mov_b32_e32 v42, v50
	v_mov_b32_e32 v44, v40
	v_mov_b32_e32 v43, v46
	v_mov_b32_e32 v45, v41
	v_add_u32_e32 v40, 0xa0, v128
	v_ashrrev_i32_e32 v41, 31, v40
	v_lshlrev_b64 v[40:41], s0, v[40:41]
	v_lshl_add_u64 v[40:41], v[40:41], 1, v[120:121]
	s_cbranch_vccnz .Lbfrag_s10
	global_store_dwordx4 v[40:41], v[42:45], off
	s_branch .Lbfrag_d10
.Lbfrag_s10:
	global_store_dwordx4 v250, v[42:45], s[98:99]
; __device__ __forceinline__ float sigm_f(float x) { return __builtin_amdgcn_rcpf(1.f + __builtin_amdgcn_exp2f(x * -1.4426950408889634f)); }
; __device__ __forceinline__ float silu_f(float x) { return x * sigm_f(x); }
; #define SCHED __builtin_amdgcn_sched_barrier(0)
; template <int ACT>
; __device__ __forceinline__ void epi_tok(f32x4 (&acc)[2][2][4][2], bf16* __restrict__ dst, int ld, int tok0, int colbase,
;                                         const float* __restrict__ bias, float scale) {
;     ...
;   _Pragma("unroll") for (int ai = 0; ai < 2; ++ai) _Pragma("unroll") for (int bj = 0; bj < 2; ++bj) _Pragma("unroll") for (int m = 0; m < 4; ++m) {
;     uint2 pk[2];
;     _Pragma("unroll") for (int n = 0; n < 2; ++n) {
;       f32x4 v = acc[ai][bj][m][n];
;       if (ACT == 0) { _Pragma("unroll") for (int j = 0; j < 4; ++j) v[j] = silu_f(v[j]); }
;       else if (ACT == 1) { float4 b = *(const float4*)(bias + colbase + bj * 128 + t.wc * 32 + n * 16 + t.fq * 4);
;         v[0] = sigm_f(v[0] + b.x); v[1] = sigm_f(v[1] + b.y); v[2] = sigm_f(v[2] + b.z); v[3] = sigm_f(v[3] + b.w); }
;       else { _Pragma("unroll") for (int j = 0; j < 4; ++j) v[j] *= scale; }
;       pk[n] = pack4(v[0], v[1], v[2], v[3]);
;     }
;     const uint2 snd = odd ? pk[0] : pk[1];
;     uint2 rcv;
;     rcv.x = (unsigned)__builtin_amdgcn_ds_bpermute(paddr, (int)snd.x);
;     rcv.y = (unsigned)__builtin_amdgcn_ds_bpermute(paddr, (int)snd.y);
;     const u32x4 outv = odd ? u32x4{rcv.x, rcv.y, pk[1].x, pk[1].y} : u32x4{pk[0].x, pk[0].y, rcv.x, rcv.y};
;     const int row = ai * 128 + t.wr * 64 + m * 16 + t.fr;
;     const int col = bj * 128 + t.wc * 32 + (odd ? 16 + (t.fq - 1) * 4 : t.fq * 4);
;     *(u32x4*)(dst + (size_t)(tok0 + row) * ld + colbase + col) = outv;
;     SCHED;
;   }
.Lbfrag_d10:
	v_add_u32_e32 v250, 0x2000, v250
	s_nop 1
	v_mul_f32_e32 v42, 0xbfb8aa3b, v36
	v_mul_f32_e32 v43, 0xbfb8aa3b, v37
	v_exp_f32_e32 v42, v42
	v_exp_f32_e32 v43, v43
	v_add_f32_e32 v42, 1.0, v42
	v_add_f32_e32 v43, 1.0, v43
	v_rcp_f32_e32 v42, v42
	v_rcp_f32_e32 v43, v43
	s_nop 0
	v_pk_mul_f32 v[36:37], v[36:37], v[42:43]
	v_mul_f32_e32 v42, 0xbfb8aa3b, v38
	v_mul_f32_e32 v43, 0xbfb8aa3b, v39
	v_exp_f32_e32 v42, v42
	v_exp_f32_e32 v43, v43
	v_add_f32_e32 v42, 1.0, v42
	v_add_f32_e32 v43, 1.0, v43
	v_rcp_f32_e32 v42, v42
	v_rcp_f32_e32 v43, v43
	s_nop 0
	v_pk_mul_f32 v[38:39], v[38:39], v[42:43]
	v_cvt_pk_bf16_f32 v42, v36, v37
	v_mul_f32_e32 v36, 0xbfb8aa3b, v32
	v_mul_f32_e32 v37, 0xbfb8aa3b, v33
	v_exp_f32_e32 v36, v36
	v_exp_f32_e32 v37, v37
	v_cvt_pk_bf16_f32 v38, v38, v39
	v_add_f32_e32 v36, 1.0, v36
	v_add_f32_e32 v37, 1.0, v37
	v_rcp_f32_e32 v36, v36
	v_rcp_f32_e32 v37, v37
	s_nop 0
	v_pk_mul_f32 v[32:33], v[32:33], v[36:37]
	v_mul_f32_e32 v36, 0xbfb8aa3b, v34
	v_mul_f32_e32 v37, 0xbfb8aa3b, v35
	v_exp_f32_e32 v36, v36
	v_exp_f32_e32 v37, v37
	v_cvt_pk_bf16_f32 v32, v32, v33
	v_add_f32_e32 v36, 1.0, v36
	v_add_f32_e32 v37, 1.0, v37
	v_rcp_f32_e32 v36, v36
	v_rcp_f32_e32 v37, v37
	s_nop 0
	v_pk_mul_f32 v[34:35], v[34:35], v[36:37]
	s_nop 0
	v_cvt_pk_bf16_f32 v33, v34, v35
	s_waitcnt lgkmcnt(0)
	s_cbranch_vccnz .Lbfrag_p11
	s_nop 1
	v_permlane16_swap_b32 v42, v32
	v_permlane16_swap_b32 v38, v33
.Lbfrag_p11:
	v_mov_b32_e32 v34, v42
	v_mov_b32_e32 v36, v32
	v_mov_b32_e32 v35, v38
	v_mov_b32_e32 v37, v33
	v_add_u32_e32 v32, 0xb0, v128
	v_ashrrev_i32_e32 v33, 31, v32
	v_lshlrev_b64 v[32:33], s0, v[32:33]
	v_lshl_add_u64 v[32:33], v[32:33], 1, v[120:121]
	s_cbranch_vccnz .Lbfrag_s11
	global_store_dwordx4 v[32:33], v[34:37], off
	s_branch .Lbfrag_d11
.Lbfrag_s11:
	global_store_dwordx4 v250, v[34:37], s[98:99]
.Lbfrag_d11:
	v_add_u32_e32 v250, 0x2000, v250
	s_nop 1
	v_mul_f32_e32 v34, 0xbfb8aa3b, v28
	v_mul_f32_e32 v35, 0xbfb8aa3b, v29
	v_exp_f32_e32 v34, v34
	v_exp_f32_e32 v35, v35
	v_add_f32_e32 v34, 1.0, v34
	v_add_f32_e32 v35, 1.0, v35
	v_rcp_f32_e32 v34, v34
	v_rcp_f32_e32 v35, v35
	s_nop 0
	v_pk_mul_f32 v[28:29], v[28:29], v[34:35]
	v_mul_f32_e32 v34, 0xbfb8aa3b, v30
	v_mul_f32_e32 v35, 0xbfb8aa3b, v31
	v_exp_f32_e32 v34, v34
	v_exp_f32_e32 v35, v35
	v_add_f32_e32 v34, 1.0, v34
	v_add_f32_e32 v35, 1.0, v35
	v_rcp_f32_e32 v34, v34
	v_rcp_f32_e32 v35, v35
	s_nop 0
	v_pk_mul_f32 v[30:31], v[30:31], v[34:35]
	v_cvt_pk_bf16_f32 v34, v28, v29
	v_mul_f32_e32 v28, 0xbfb8aa3b, v24
	v_mul_f32_e32 v29, 0xbfb8aa3b, v25
	v_exp_f32_e32 v28, v28
	v_exp_f32_e32 v29, v29
	v_cvt_pk_bf16_f32 v30, v30, v31
	v_add_f32_e32 v28, 1.0, v28
	v_add_f32_e32 v29, 1.0, v29
	v_rcp_f32_e32 v28, v28
	v_rcp_f32_e32 v29, v29
	s_nop 0
	v_pk_mul_f32 v[24:25], v[24:25], v[28:29]
	v_mul_f32_e32 v28, 0xbfb8aa3b, v26
	v_mul_f32_e32 v29, 0xbfb8aa3b, v27
	v_exp_f32_e32 v28, v28
	v_exp_f32_e32 v29, v29
	v_cvt_pk_bf16_f32 v24, v24, v25
	v_add_f32_e32 v28, 1.0, v28
	v_add_f32_e32 v29, 1.0, v29
	v_rcp_f32_e32 v28, v28
	v_rcp_f32_e32 v29, v29
	s_nop 0
	v_pk_mul_f32 v[26:27], v[26:27], v[28:29]
	s_nop 0
	v_cvt_pk_bf16_f32 v25, v26, v27
	s_waitcnt lgkmcnt(0)
	s_cbranch_vccnz .Lbfrag_p12
	s_nop 1
	v_permlane16_swap_b32 v34, v24
	v_permlane16_swap_b32 v30, v25
.Lbfrag_p12:
	v_mov_b32_e32 v26, v24
	v_mov_b32_e32 v24, v34
	v_mov_b32_e32 v27, v25
	v_mov_b32_e32 v25, v30
	s_cbranch_vccnz .Lbfrag_s12
	global_store_dwordx4 v[56:57], v[24:27], off offset:256
	s_branch .Lbfrag_d12
.Lbfrag_s12:
	global_store_dwordx4 v250, v[24:27], s[98:99]
.Lbfrag_d12:
	v_add_u32_e32 v250, 0x2000, v250
	s_nop 1
	v_mul_f32_e32 v24, 0xbfb8aa3b, v20
	v_mul_f32_e32 v25, 0xbfb8aa3b, v21
	v_exp_f32_e32 v24, v24
	v_exp_f32_e32 v25, v25
	v_add_f32_e32 v24, 1.0, v24
	v_add_f32_e32 v25, 1.0, v25
	v_rcp_f32_e32 v24, v24
	v_rcp_f32_e32 v25, v25
	s_nop 0
	v_pk_mul_f32 v[20:21], v[20:21], v[24:25]
	v_mul_f32_e32 v24, 0xbfb8aa3b, v22
	v_mul_f32_e32 v25, 0xbfb8aa3b, v23
	v_exp_f32_e32 v24, v24
	v_exp_f32_e32 v25, v25
	v_add_f32_e32 v24, 1.0, v24
	v_add_f32_e32 v25, 1.0, v25
	v_rcp_f32_e32 v24, v24
	v_rcp_f32_e32 v25, v25
	s_nop 0
	v_pk_mul_f32 v[22:23], v[22:23], v[24:25]
	v_cvt_pk_bf16_f32 v24, v20, v21
	v_mul_f32_e32 v20, 0xbfb8aa3b, v16
	v_mul_f32_e32 v21, 0xbfb8aa3b, v17
	v_exp_f32_e32 v20, v20
	v_exp_f32_e32 v21, v21
	v_cvt_pk_bf16_f32 v22, v22, v23
	v_add_f32_e32 v20, 1.0, v20
	v_add_f32_e32 v21, 1.0, v21
	v_rcp_f32_e32 v20, v20
	v_rcp_f32_e32 v21, v21
	s_nop 0
	v_pk_mul_f32 v[16:17], v[16:17], v[20:21]
	v_mul_f32_e32 v20, 0xbfb8aa3b, v18
	v_mul_f32_e32 v21, 0xbfb8aa3b, v19
	v_exp_f32_e32 v20, v20
	v_exp_f32_e32 v21, v21
	v_cvt_pk_bf16_f32 v16, v16, v17
	v_add_f32_e32 v20, 1.0, v20
	v_add_f32_e32 v21, 1.0, v21
	v_rcp_f32_e32 v20, v20
	v_rcp_f32_e32 v21, v21
	s_nop 0
	v_pk_mul_f32 v[18:19], v[18:19], v[20:21]
	s_nop 0
	v_cvt_pk_bf16_f32 v17, v18, v19
	s_waitcnt lgkmcnt(0)
	s_cbranch_vccnz .Lbfrag_p13
	s_nop 1
	v_permlane16_swap_b32 v24, v16
	v_permlane16_swap_b32 v22, v17
; __device__ __forceinline__ float sigm_f(float x) { return __builtin_amdgcn_rcpf(1.f + __builtin_amdgcn_exp2f(x * -1.4426950408889634f)); }
; __device__ __forceinline__ float silu_f(float x) { return x * sigm_f(x); }
; #define SCHED __builtin_amdgcn_sched_barrier(0)
; template <int ACT>
; __device__ __forceinline__ void epi_tok(f32x4 (&acc)[2][2][4][2], bf16* __restrict__ dst, int ld, int tok0, int colbase,
;                                         const float* __restrict__ bias, float scale) {
;     ...
;   _Pragma("unroll") for (int ai = 0; ai < 2; ++ai) _Pragma("unroll") for (int bj = 0; bj < 2; ++bj) _Pragma("unroll") for (int m = 0; m < 4; ++m) {
;     uint2 pk[2];
;     _Pragma("unroll") for (int n = 0; n < 2; ++n) {
;       f32x4 v = acc[ai][bj][m][n];
;       if (ACT == 0) { _Pragma("unroll") for (int j = 0; j < 4; ++j) v[j] = silu_f(v[j]); }
;       else if (ACT == 1) { float4 b = *(const float4*)(bias + colbase + bj * 128 + t.wc * 32 + n * 16 + t.fq * 4);
;         v[0] = sigm_f(v[0] + b.x); v[1] = sigm_f(v[1] + b.y); v[2] = sigm_f(v[2] + b.z); v[3] = sigm_f(v[3] + b.w); }
;       else { _Pragma("unroll") for (int j = 0; j < 4; ++j) v[j] *= scale; }
;       pk[n] = pack4(v[0], v[1], v[2], v[3]);
;     }
;     const uint2 snd = odd ? pk[0] : pk[1];
;     uint2 rcv;
;     rcv.x = (unsigned)__builtin_amdgcn_ds_bpermute(paddr, (int)snd.x);
;     rcv.y = (unsigned)__builtin_amdgcn_ds_bpermute(paddr, (int)snd.y);
;     const u32x4 outv = odd ? u32x4{rcv.x, rcv.y, pk[1].x, pk[1].y} : u32x4{pk[0].x, pk[0].y, rcv.x, rcv.y};
;     const int row = ai * 128 + t.wr * 64 + m * 16 + t.fr;
;     const int col = bj * 128 + t.wc * 32 + (odd ? 16 + (t.fq - 1) * 4 : t.fq * 4);
;     *(u32x4*)(dst + (size_t)(tok0 + row) * ld + colbase + col) = outv;
;     SCHED;
;   }
.Lbfrag_p13:
	v_mov_b32_e32 v18, v16
	v_mov_b32_e32 v16, v24
	v_mov_b32_e32 v19, v17
	v_mov_b32_e32 v17, v22
	s_cbranch_vccnz .Lbfrag_s13
	global_store_dwordx4 v[48:49], v[16:19], off offset:256
	s_branch .Lbfrag_d13
.Lbfrag_s13:
	global_store_dwordx4 v250, v[16:19], s[98:99]
.Lbfrag_d13:
	v_add_u32_e32 v250, 0x2000, v250
	s_nop 1
	v_mul_f32_e32 v16, 0xbfb8aa3b, v12
	v_mul_f32_e32 v17, 0xbfb8aa3b, v13
	v_exp_f32_e32 v16, v16
	v_exp_f32_e32 v17, v17
	v_add_f32_e32 v16, 1.0, v16
	v_add_f32_e32 v17, 1.0, v17
	v_rcp_f32_e32 v16, v16
	v_rcp_f32_e32 v17, v17
	s_nop 0
	v_pk_mul_f32 v[12:13], v[12:13], v[16:17]
	v_mul_f32_e32 v16, 0xbfb8aa3b, v14
	v_mul_f32_e32 v17, 0xbfb8aa3b, v15
	v_exp_f32_e32 v16, v16
	v_exp_f32_e32 v17, v17
	v_add_f32_e32 v16, 1.0, v16
	v_add_f32_e32 v17, 1.0, v17
	v_rcp_f32_e32 v16, v16
	v_rcp_f32_e32 v17, v17
	s_nop 0
	v_pk_mul_f32 v[14:15], v[14:15], v[16:17]
	v_cvt_pk_bf16_f32 v16, v12, v13
	v_mul_f32_e32 v12, 0xbfb8aa3b, v8
	v_mul_f32_e32 v13, 0xbfb8aa3b, v9
	v_exp_f32_e32 v12, v12
	v_exp_f32_e32 v13, v13
	v_cvt_pk_bf16_f32 v14, v14, v15
	v_add_f32_e32 v12, 1.0, v12
	v_add_f32_e32 v13, 1.0, v13
	v_rcp_f32_e32 v12, v12
	v_rcp_f32_e32 v13, v13
	s_nop 0
	v_pk_mul_f32 v[8:9], v[8:9], v[12:13]
	v_mul_f32_e32 v12, 0xbfb8aa3b, v10
	v_mul_f32_e32 v13, 0xbfb8aa3b, v11
	v_exp_f32_e32 v12, v12
	v_exp_f32_e32 v13, v13
	v_cvt_pk_bf16_f32 v8, v8, v9
	v_add_f32_e32 v12, 1.0, v12
	v_add_f32_e32 v13, 1.0, v13
	v_rcp_f32_e32 v12, v12
	v_rcp_f32_e32 v13, v13
	s_nop 0
	v_pk_mul_f32 v[10:11], v[10:11], v[12:13]
	s_nop 0
	v_cvt_pk_bf16_f32 v9, v10, v11
	s_waitcnt lgkmcnt(0)
	s_cbranch_vccnz .Lbfrag_p14
	s_nop 1
	v_permlane16_swap_b32 v16, v8
	v_permlane16_swap_b32 v14, v9
.Lbfrag_p14:
	v_mov_b32_e32 v10, v8
	v_mov_b32_e32 v8, v16
	v_mov_b32_e32 v11, v9
	v_mov_b32_e32 v9, v14
	s_cbranch_vccnz .Lbfrag_s14
	global_store_dwordx4 v[40:41], v[8:11], off offset:256
	s_branch .Lbfrag_d14
.Lbfrag_s14:
	global_store_dwordx4 v250, v[8:11], s[98:99]
.Lbfrag_d14:
	v_add_u32_e32 v250, 0x2000, v250
	s_nop 1
	v_mul_f32_e32 v8, 0xbfb8aa3b, v4
	v_mul_f32_e32 v9, 0xbfb8aa3b, v5
	v_exp_f32_e32 v8, v8
	v_exp_f32_e32 v9, v9
	v_add_f32_e32 v8, 1.0, v8
	v_add_f32_e32 v9, 1.0, v9
	v_rcp_f32_e32 v8, v8
	v_rcp_f32_e32 v9, v9
	s_nop 0
	v_pk_mul_f32 v[4:5], v[4:5], v[8:9]
	v_mul_f32_e32 v8, 0xbfb8aa3b, v6
	v_mul_f32_e32 v9, 0xbfb8aa3b, v7
	v_exp_f32_e32 v8, v8
	v_exp_f32_e32 v9, v9
	v_add_f32_e32 v8, 1.0, v8
	v_add_f32_e32 v9, 1.0, v9
	v_rcp_f32_e32 v8, v8
	v_rcp_f32_e32 v9, v9
	s_nop 0
	v_pk_mul_f32 v[6:7], v[6:7], v[8:9]
	v_cvt_pk_bf16_f32 v8, v4, v5
	v_mul_f32_e32 v4, 0xbfb8aa3b, v0
	v_mul_f32_e32 v5, 0xbfb8aa3b, v1
	v_exp_f32_e32 v4, v4
	v_exp_f32_e32 v5, v5
	v_cvt_pk_bf16_f32 v6, v6, v7
	v_add_f32_e32 v4, 1.0, v4
	v_add_f32_e32 v5, 1.0, v5
	v_rcp_f32_e32 v4, v4
	v_rcp_f32_e32 v5, v5
	s_nop 0
	v_pk_mul_f32 v[0:1], v[0:1], v[4:5]
	v_mul_f32_e32 v4, 0xbfb8aa3b, v2
	v_mul_f32_e32 v5, 0xbfb8aa3b, v3
	v_exp_f32_e32 v4, v4
	v_exp_f32_e32 v5, v5
	v_cvt_pk_bf16_f32 v0, v0, v1
	v_add_f32_e32 v4, 1.0, v4
	v_add_f32_e32 v5, 1.0, v5
	v_rcp_f32_e32 v4, v4
	v_rcp_f32_e32 v5, v5
	s_nop 0
	v_pk_mul_f32 v[2:3], v[2:3], v[4:5]
	s_nop 0
	v_cvt_pk_bf16_f32 v1, v2, v3
	s_waitcnt lgkmcnt(0)
	s_cbranch_vccnz .Lbfrag_p15
	s_nop 1
	v_permlane16_swap_b32 v8, v0
	v_permlane16_swap_b32 v6, v1
.Lbfrag_p15:
	v_mov_b32_e32 v2, v0
	v_mov_b32_e32 v0, v8
	v_mov_b32_e32 v3, v1
	v_mov_b32_e32 v1, v6
	s_cbranch_vccnz .Lbfrag_s15
	global_store_dwordx4 v[32:33], v[0:3], off offset:256
	s_branch .Lbfrag_d15
.Lbfrag_s15:
	global_store_dwordx4 v250, v[0:3], s[98:99]
.Lbfrag_d15:
	v_add_u32_e32 v250, 0x2000, v250
	s_mov_b64 s[14:15], -1
	s_and_b64 vcc, exec, s[4:5]
	s_cbranch_vccnz .LBB0_519

; __device__ __forceinline__ void phase_attn(const Params& p, const Grp& g, int l) {
;     ...
;     u32x4 zreg[4];
;     if (last_of_item) {
;       const bf16* zp = SZA + (size_t)((c_bl << g.lgS) + c_qb * 128 + qrow0 + fr) * 1024 + c_h * 128 + fq * 4;
;       _Pragma("unroll") for (int i = 0; i < 4; ++i) {
;         uint2 a = *(const uint2*)(zp + (2 * i) * 16), b = *(const uint2*)(zp + (2 * i + 1) * 16);
;         zreg[i] = u32x4{a.x, a.y, b.x, b.y};
;       }
.Lattn_skip_kv:
	v_cndmask_b32_e64 v112, 0, 1, s[10:11]
	v_mov_b32_e32 v148, 0
	v_cmp_ne_u32_e64 s[4:5], 1, v112
	s_andn2_b64 vcc, exec, s[10:11]
	v_lshlrev_b32_e32 v158, 1, v144
	v_mov_b32_e32 v149, 0
	v_mov_b32_e32 v146, 0
	v_mov_b32_e32 v147, 0
	v_mov_b32_e32 v152, 0
	v_mov_b32_e32 v153, 0
	v_mov_b32_e32 v150, 0
	v_mov_b32_e32 v151, 0
	v_mov_b32_e32 v156, 0
	v_mov_b32_e32 v157, 0
	v_mov_b32_e32 v154, 0
	v_mov_b32_e32 v155, 0
	v_mov_b32_e32 v162, 0
	v_mov_b32_e32 v163, 0
	v_mov_b32_e32 v160, 0
	v_mov_b32_e32 v161, 0
	s_cbranch_vccnz .LBB0_741
	global_load_dwordx4 v[48:51], v[60:61], off
	global_load_dwordx4 v[52:55], v[60:61], off offset:64
	global_load_dwordx4 v[56:59], v[60:61], off offset:128
	s_nop 0
	global_load_dwordx4 v[60:63], v[60:61], off offset:192
	s_add_i32 s0, s40, -8
	s_lshl_b32 s0, s65, s0
	s_lshr_b32 s1, s66, 1
	s_add_i32 s0, s0, s1
	s_lshl_b32 s0, s0, 2
	s_lshr_b32 s1, s63, 1
	s_add_i32 s0, s0, s1
	s_lshl_b32 s0, s0, 17
	s_and_b32 s1, s66, 1
	s_lshl_b32 s1, s1, 1
	s_and_b32 s20, s63, 1
	s_add_i32 s1, s1, s20
	s_lshl_b32 s1, s1, 15
	s_add_i32 s0, s0, s1
	s_add_u32 s0, s8, s0
	s_addc_u32 s1, s9, 0
	v_and_b32_e32 v112, 0xc0, v190
	v_lshlrev_b32_e32 v112, 7, v112
	v_and_b32_e32 v113, 0x100, v190
	v_lshl_or_b32 v112, v113, 4, v112
	v_and_b32_e32 v113, 63, v190
	v_lshl_or_b32 v112, v113, 4, v112
	v_mov_b32_e32 v159, v187
	global_load_dwordx4 v[160:163], v112, s[0:1]
	global_load_dwordx4 v[154:157], v112, s[0:1] offset:1024
	global_load_dwordx4 v[150:153], v112, s[0:1] offset:2048
	global_load_dwordx4 v[146:149], v112, s[0:1] offset:3072

; __device__ __forceinline__ void phase_attn(const Params& p, const Grp& g, int l) {
;     ...
;     {
;       float mx = -1e30f;
;       _Pragma("unroll") for (int kt = 0; kt < 8; ++kt) _Pragma("unroll") for (int r = 0; r < 4; ++r) mx = fmaxf(mx, s[kt][r]);
;       mx = fmaxf(mx, shfl_xor_l(mx, 16, lane)); mx = fmaxf(mx, shfl_xor_l(mx, 32, lane));
;       float mnew = fmaxf(mrun, mx);
;       float alpha = __builtin_amdgcn_exp2f(mrun - mnew);
;       mrun = mnew; lrun *= alpha;
;       const float alpha_o = first_ ? 0.f : alpha;
;       _Pragma("unroll") for (int dt = 0; dt < 8; ++dt) _Pragma("unroll") for (int r = 0; r < 4; ++r) o[dt][r] *= alpha_o;
;       float ls = 0.f;
;       _Pragma("unroll") for (int kt = 0; kt < 8; ++kt) _Pragma("unroll") for (int r = 0; r < 4; ++r) { float pv = __builtin_amdgcn_exp2f(s[kt][r] - mnew); s[kt][r] = pv; ls += pv; }
;       lrun += ls;
;     }
;     {
;       bf16x8 pf[4];
;       _Pragma("unroll") for (int kp = 0; kp < 4; ++kp) {
;         uint2 plo = pack4(s[2 * kp][0], s[2 * kp][1], s[2 * kp][2], s[2 * kp][3]);
;         uint2 phi = pack4(s[2 * kp + 1][0], s[2 * kp + 1][1], s[2 * kp + 1][2], s[2 * kp + 1][3]);
;         u32x4 pu = {plo.x, plo.y, phi.x, phi.y};
;         pf[kp] = __builtin_bit_cast(bf16x8, pu);
;       }
;       bf16x8 vf[2][4];
;       const char* vbase = Vs + fr * KPITCH + fq * 16;
;       _Pragma("unroll") for (int j = 0; j < 4; ++j) vf[0][j] = *(const bf16x8*)(vbase + (j * 16) * KPITCH);
;       _Pragma("unroll") for (int idx = 0; idx < 8; ++idx) {
;         if (idx < 7) {
;           const int nk = (idx + 1) >> 1, nd = (idx + 1) & 1;
;           _Pragma("unroll") for (int j = 0; j < 4; ++j)
;             vf[(idx + 1) & 1][j] = *(const bf16x8*)(vbase + ((nd * 4 + j) * 16) * KPITCH + nk * 64);
;         }
;         __builtin_amdgcn_s_setprio(1);
;         _Pragma("unroll") for (int j = 0; j < 4; ++j)
;           o[(idx & 1) * 4 + j] = __builtin_amdgcn_mfma_f32_16x16x32_bf16(vf[idx & 1][j], pf[idx >> 1], o[(idx & 1) * 4 + j], 0, 0, 0);
;         __builtin_amdgcn_s_setprio(0);
;       }
.LBB0_747:
	s_mov_b32 s0, 0xf149f2ca
	v_max3_f32 v96, v220, s0, v219
	v_max3_f32 v96, v96, v218, v217
	v_max3_f32 v96, v96, v216, v215
	v_max3_f32 v96, v96, v214, v213
	v_max3_f32 v96, v96, v212, v211
	v_max3_f32 v96, v96, v210, v209
	v_max3_f32 v96, v96, v208, v207
	v_max3_f32 v96, v96, v206, v205
	v_max3_f32 v96, v96, v204, v203
	v_max3_f32 v96, v96, v202, v201
	v_max3_f32 v96, v96, v200, v199
	v_max3_f32 v96, v96, v198, v189
	v_max3_f32 v96, v96, v188, v179
	v_max3_f32 v96, v96, v178, v177
	v_max3_f32 v96, v96, v173, v174
	v_max3_f32 v96, v96, v175, v176
	ds_bpermute_b32 v97, v168, v96
	s_waitcnt lgkmcnt(0)
	v_max_f32_e32 v97, v97, v97
	v_max_f32_e32 v96, v96, v97
	ds_bpermute_b32 v97, v169, v96
	s_waitcnt lgkmcnt(0)
	v_max3_f32 v112, v172, v96, v97
	v_sub_f32_e32 v96, v172, v112
	v_exp_f32_e32 v126, v96
	v_sub_f32_e32 v98, v219, v112
	v_exp_f32_e32 v98, v98
	v_sub_f32_e32 v99, v218, v112
	v_cndmask_b32_e64 v96, v126, 0, s[14:15]
	v_pk_mul_f32 v[94:95], v[94:95], v[96:97] op_sel_hi:[1,0]
	v_pk_mul_f32 v[92:93], v[92:93], v[96:97] op_sel_hi:[1,0]
	v_pk_mul_f32 v[90:91], v[90:91], v[96:97] op_sel_hi:[1,0]
	v_pk_mul_f32 v[88:89], v[88:89], v[96:97] op_sel_hi:[1,0]
	v_pk_mul_f32 v[86:87], v[86:87], v[96:97] op_sel_hi:[1,0]
	v_pk_mul_f32 v[84:85], v[84:85], v[96:97] op_sel_hi:[1,0]
	v_pk_mul_f32 v[82:83], v[82:83], v[96:97] op_sel_hi:[1,0]
	v_pk_mul_f32 v[80:81], v[80:81], v[96:97] op_sel_hi:[1,0]
	v_pk_mul_f32 v[78:79], v[78:79], v[96:97] op_sel_hi:[1,0]
	v_pk_mul_f32 v[76:77], v[76:77], v[96:97] op_sel_hi:[1,0]
	v_pk_mul_f32 v[74:75], v[74:75], v[96:97] op_sel_hi:[1,0]
	v_pk_mul_f32 v[72:73], v[72:73], v[96:97] op_sel_hi:[1,0]
	v_pk_mul_f32 v[70:71], v[70:71], v[96:97] op_sel_hi:[1,0]
	v_pk_mul_f32 v[68:69], v[68:69], v[96:97] op_sel_hi:[1,0]
	v_pk_mul_f32 v[66:67], v[66:67], v[96:97] op_sel_hi:[1,0]
	v_pk_mul_f32 v[64:65], v[64:65], v[96:97] op_sel_hi:[1,0]
	v_sub_f32_e32 v96, v220, v112
	v_exp_f32_e32 v96, v96
	v_exp_f32_e32 v99, v99
	v_sub_f32_e32 v100, v217, v112
	v_exp_f32_e32 v100, v100
	v_sub_f32_e32 v101, v216, v112
	v_add_f32_e32 v97, 0, v96
	v_exp_f32_e32 v101, v101
	v_sub_f32_e32 v102, v215, v112
	v_add_f32_e32 v97, v98, v97
	v_exp_f32_e32 v102, v102
	v_sub_f32_e32 v103, v214, v112
	v_add_f32_e32 v97, v99, v97
	v_exp_f32_e32 v103, v103
	v_sub_f32_e32 v104, v213, v112
	v_add_f32_e32 v97, v100, v97
	v_exp_f32_e32 v104, v104
	v_sub_f32_e32 v105, v212, v112
	v_add_f32_e32 v97, v101, v97
	v_exp_f32_e32 v105, v105
	v_sub_f32_e32 v106, v211, v112
	v_add_f32_e32 v97, v102, v97
	v_exp_f32_e32 v106, v106
	v_sub_f32_e32 v107, v210, v112
	v_add_f32_e32 v97, v103, v97
	v_exp_f32_e32 v107, v107
	v_sub_f32_e32 v108, v209, v112
	v_add_f32_e32 v97, v104, v97
	v_exp_f32_e32 v108, v108
	v_sub_f32_e32 v109, v208, v112
	v_add_f32_e32 v97, v105, v97
	v_exp_f32_e32 v109, v109
	v_sub_f32_e32 v110, v207, v112
	v_add_f32_e32 v97, v106, v97
	v_exp_f32_e32 v110, v110
	v_sub_f32_e32 v111, v206, v112
	v_add_f32_e32 v97, v107, v97
	v_exp_f32_e32 v111, v111
	v_sub_f32_e32 v113, v205, v112
	v_add_f32_e32 v97, v108, v97
	v_exp_f32_e32 v113, v113
	v_sub_f32_e32 v114, v204, v112
	v_add_f32_e32 v97, v109, v97
	v_exp_f32_e32 v114, v114
	v_sub_f32_e32 v115, v203, v112
	v_add_f32_e32 v97, v110, v97
	v_exp_f32_e32 v115, v115
	v_sub_f32_e32 v116, v202, v112
	v_add_f32_e32 v97, v111, v97
	v_exp_f32_e32 v116, v116
	v_sub_f32_e32 v117, v201, v112
	v_add_f32_e32 v97, v113, v97
	v_exp_f32_e32 v117, v117
	v_sub_f32_e32 v118, v200, v112
	v_add_f32_e32 v97, v114, v97
	v_exp_f32_e32 v118, v118
	v_sub_f32_e32 v119, v199, v112
	v_add_f32_e32 v97, v115, v97
	v_exp_f32_e32 v119, v119
	v_sub_f32_e32 v120, v198, v112
	v_add_f32_e32 v97, v116, v97
	v_exp_f32_e32 v120, v120
	v_sub_f32_e32 v121, v189, v112
	v_add_f32_e32 v97, v117, v97
	v_exp_f32_e32 v121, v121
	v_sub_f32_e32 v122, v188, v112
	v_add_f32_e32 v97, v118, v97
	v_exp_f32_e32 v122, v122
	v_sub_f32_e32 v123, v179, v112
	v_add_f32_e32 v97, v119, v97
	v_exp_f32_e32 v123, v123
	v_sub_f32_e32 v124, v178, v112
	v_add_f32_e32 v97, v120, v97
	v_exp_f32_e32 v124, v124
	v_sub_f32_e32 v125, v177, v112
	v_add_f32_e32 v97, v121, v97
	v_exp_f32_e32 v125, v125
	v_add_f32_e32 v97, v122, v97
	v_add_f32_e32 v97, v123, v97
	v_add_f32_e32 v97, v124, v97
	v_add_f32_e32 v127, v125, v97
	v_sub_f32_e32 v97, v173, v112
	v_exp_f32_e32 v172, v97
	v_sub_f32_e32 v97, v174, v112
	v_exp_f32_e32 v173, v97
	v_sub_f32_e32 v97, v175, v112
	v_exp_f32_e32 v174, v97
	v_sub_f32_e32 v97, v176, v112
	v_exp_f32_e32 v175, v97
	v_cvt_pk_bf16_f32 v97, v99, v100
	v_cvt_pk_bf16_f32 v99, v103, v104
	v_cvt_pk_bf16_f32 v103, v111, v113
	v_add_f32_e32 v113, v172, v127
	v_add_f32_e32 v113, v173, v113
	v_add_f32_e32 v113, v174, v113
	v_cvt_pk_bf16_f32 v96, v96, v98
	v_cvt_pk_bf16_f32 v98, v101, v102
	v_cvt_pk_bf16_f32 v100, v105, v106
	v_cvt_pk_bf16_f32 v101, v107, v108
	v_cvt_pk_bf16_f32 v102, v109, v110
	v_cvt_pk_bf16_f32 v104, v114, v115
	v_cvt_pk_bf16_f32 v105, v116, v117
	v_cvt_pk_bf16_f32 v106, v118, v119
	v_cvt_pk_bf16_f32 v107, v120, v121
	v_cvt_pk_bf16_f32 v108, v122, v123
	v_cvt_pk_bf16_f32 v109, v124, v125
	v_cvt_pk_bf16_f32 v110, v172, v173
	v_cvt_pk_bf16_f32 v111, v174, v175
	v_add_f32_e32 v113, v175, v113
	ds_read_b128 v[114:117], v159 offset:34816
	ds_read_b128 v[118:121], v159 offset:39168
	ds_read_b128 v[122:125], v159 offset:43520
	ds_read_b128 v[172:175], v159 offset:47872
	ds_read_b128 v[176:179], v159 offset:52224
	ds_read_b128 v[198:201], v159 offset:56576
	ds_read_b128 v[202:205], v159 offset:60928
	ds_read_b128 v[206:209], v159 offset:65280
	s_setprio 1
	s_waitcnt lgkmcnt(7)
	v_mfma_f32_16x16x32_bf16 v[92:95], v[114:117], v[96:99], v[92:95]
	s_waitcnt lgkmcnt(6)
; __device__ __forceinline__ void phase_attn(const Params& p, const Grp& g, int l) {
;     ...
;       bf16x8 vf[2][4];
;       const char* vbase = Vs + fr * KPITCH + fq * 16;
;       _Pragma("unroll") for (int j = 0; j < 4; ++j) vf[0][j] = *(const bf16x8*)(vbase + (j * 16) * KPITCH);
;       _Pragma("unroll") for (int idx = 0; idx < 8; ++idx) {
;         if (idx < 7) {
;           const int nk = (idx + 1) >> 1, nd = (idx + 1) & 1;
;           _Pragma("unroll") for (int j = 0; j < 4; ++j)
;             vf[(idx + 1) & 1][j] = *(const bf16x8*)(vbase + ((nd * 4 + j) * 16) * KPITCH + nk * 64);
;         }
;         __builtin_amdgcn_s_setprio(1);
;         _Pragma("unroll") for (int j = 0; j < 4; ++j)
;           o[(idx & 1) * 4 + j] = __builtin_amdgcn_mfma_f32_16x16x32_bf16(vf[idx & 1][j], pf[idx >> 1], o[(idx & 1) * 4 + j], 0, 0, 0);
;         __builtin_amdgcn_s_setprio(0);
;       }
	v_mfma_f32_16x16x32_bf16 v[88:91], v[118:121], v[96:99], v[88:91]
	s_waitcnt lgkmcnt(5)
	v_mfma_f32_16x16x32_bf16 v[84:87], v[122:125], v[96:99], v[84:87]
	s_waitcnt lgkmcnt(4)
	v_mfma_f32_16x16x32_bf16 v[80:83], v[172:175], v[96:99], v[80:83]
	s_setprio 0
	ds_read_b128 v[114:117], v159 offset:34880
	ds_read_b128 v[118:121], v159 offset:39232
	ds_read_b128 v[122:125], v159 offset:43584
	ds_read_b128 v[172:175], v159 offset:47936
	s_setprio 1
	s_waitcnt lgkmcnt(7)
	v_mfma_f32_16x16x32_bf16 v[76:79], v[176:179], v[96:99], v[76:79]
	s_waitcnt lgkmcnt(6)
	v_mfma_f32_16x16x32_bf16 v[72:75], v[198:201], v[96:99], v[72:75]
	s_waitcnt lgkmcnt(5)
	v_mfma_f32_16x16x32_bf16 v[68:71], v[202:205], v[96:99], v[68:71]
	s_waitcnt lgkmcnt(4)
	v_mfma_f32_16x16x32_bf16 v[64:67], v[206:209], v[96:99], v[64:67]
	s_setprio 0
	ds_read_b128 v[96:99], v159 offset:52288
	ds_read_b128 v[176:179], v159 offset:56640
	ds_read_b128 v[198:201], v159 offset:60992
	ds_read_b128 v[202:205], v159 offset:65344
	s_setprio 1
	s_waitcnt lgkmcnt(7)
	v_mfma_f32_16x16x32_bf16 v[92:95], v[114:117], v[100:103], v[92:95]
	s_waitcnt lgkmcnt(6)
	v_mfma_f32_16x16x32_bf16 v[88:91], v[118:121], v[100:103], v[88:91]
	s_waitcnt lgkmcnt(5)
	v_mfma_f32_16x16x32_bf16 v[84:87], v[122:125], v[100:103], v[84:87]
	s_waitcnt lgkmcnt(4)
	v_mfma_f32_16x16x32_bf16 v[80:83], v[172:175], v[100:103], v[80:83]
	s_setprio 0
	ds_read_b128 v[114:117], v159 offset:34944
	ds_read_b128 v[118:121], v159 offset:39296
	ds_read_b128 v[122:125], v159 offset:43648
	ds_read_b128 v[172:175], v159 offset:48000
	s_setprio 1
	s_waitcnt lgkmcnt(7)
	v_mfma_f32_16x16x32_bf16 v[76:79], v[96:99], v[100:103], v[76:79]
	s_waitcnt lgkmcnt(6)
	v_mfma_f32_16x16x32_bf16 v[72:75], v[176:179], v[100:103], v[72:75]
	s_waitcnt lgkmcnt(5)
	v_mfma_f32_16x16x32_bf16 v[68:71], v[198:201], v[100:103], v[68:71]
	s_waitcnt lgkmcnt(4)
	v_mfma_f32_16x16x32_bf16 v[64:67], v[202:205], v[100:103], v[64:67]
	s_setprio 0
	ds_read_b128 v[96:99], v159 offset:52352
	ds_read_b128 v[100:103], v159 offset:56704
	ds_read_b128 v[176:179], v159 offset:61056
	ds_read_b128 v[198:201], v159 offset:65408
	s_setprio 1
	s_waitcnt lgkmcnt(7)
	v_mfma_f32_16x16x32_bf16 v[92:95], v[114:117], v[104:107], v[92:95]
	s_waitcnt lgkmcnt(6)
	v_mfma_f32_16x16x32_bf16 v[88:91], v[118:121], v[104:107], v[88:91]
	s_waitcnt lgkmcnt(5)
	v_mfma_f32_16x16x32_bf16 v[84:87], v[122:125], v[104:107], v[84:87]
	s_waitcnt lgkmcnt(4)
	v_mfma_f32_16x16x32_bf16 v[80:83], v[172:175], v[104:107], v[80:83]
	s_setprio 0
	ds_read_b128 v[114:117], v159 offset:35008
	ds_read_b128 v[118:121], v159 offset:39360
	ds_read_b128 v[122:125], v159 offset:43712
	ds_read_b128 v[172:175], v159 offset:48064
	s_setprio 1
	s_waitcnt lgkmcnt(7)
	v_mfma_f32_16x16x32_bf16 v[76:79], v[96:99], v[104:107], v[76:79]
	s_waitcnt lgkmcnt(6)
	v_mfma_f32_16x16x32_bf16 v[72:75], v[100:103], v[104:107], v[72:75]
	s_waitcnt lgkmcnt(5)
	v_mfma_f32_16x16x32_bf16 v[68:71], v[176:179], v[104:107], v[68:71]
	s_waitcnt lgkmcnt(4)
	v_mfma_f32_16x16x32_bf16 v[64:67], v[198:201], v[104:107], v[64:67]
	s_setprio 0
	ds_read_b128 v[96:99], v159 offset:52416
	ds_read_b128 v[100:103], v159 offset:56768
	ds_read_b128 v[104:107], v159 offset:61120
	ds_read_b128 v[176:179], v159 offset:65472
	s_setprio 1
	s_waitcnt lgkmcnt(7)
	v_mfma_f32_16x16x32_bf16 v[92:95], v[114:117], v[108:111], v[92:95]
	s_waitcnt lgkmcnt(6)
	v_mfma_f32_16x16x32_bf16 v[88:91], v[118:121], v[108:111], v[88:91]
	s_waitcnt lgkmcnt(5)
	v_mfma_f32_16x16x32_bf16 v[84:87], v[122:125], v[108:111], v[84:87]
	s_waitcnt lgkmcnt(4)
	v_mfma_f32_16x16x32_bf16 v[80:83], v[172:175], v[108:111], v[80:83]
	s_setprio 0
	s_setprio 1
	s_waitcnt lgkmcnt(3)
	v_mfma_f32_16x16x32_bf16 v[76:79], v[96:99], v[108:111], v[76:79]
	s_waitcnt lgkmcnt(2)
	v_mfma_f32_16x16x32_bf16 v[72:75], v[100:103], v[108:111], v[72:75]
	s_waitcnt lgkmcnt(1)
	v_mfma_f32_16x16x32_bf16 v[68:71], v[104:107], v[108:111], v[68:71]
	s_waitcnt lgkmcnt(0)
	v_mfma_f32_16x16x32_bf16 v[64:67], v[176:179], v[108:111], v[64:67]
	s_setprio 0
	s_and_b64 vcc, exec, s[4:5]
	v_fmac_f32_e32 v113, v171, v126
	s_cbranch_vccnz .LBB0_730
; __device__ __forceinline__ void phase_attn(const Params& p, const Grp& g, int l) {
;     ...
;     if (last_of_item) {
;       float lsum = lrun;
;       lsum += shfl_xor_l(lsum, 16, lane); lsum += shfl_xor_l(lsum, 32, lane);
;       float inv = __builtin_amdgcn_rcpf(lsum);
;       size_t rowb = (size_t)((c_bl << g.lgS) + c_qb * 128 + qrow0 + fr) * 1024 + c_h * 128;
;       _Pragma("unroll") for (int dt = 0; dt < 8; ++dt) {
;         size_t idx = rowb + dt * 16 + fq * 4;
;         float z0, z1, z2, z3;
;         unpack4((dt & 1) ? make_uint2(zreg[dt >> 1][2], zreg[dt >> 1][3]) : make_uint2(zreg[dt >> 1][0], zreg[dt >> 1][1]), z0, z1, z2, z3);
;         *(uint2*)(YA + idx) = pack4(o[dt][0] * inv * z0, o[dt][1] * inv * z1, o[dt][2] * inv * z2, o[dt][3] * inv * z3);
;       }
;     }
;     first = last_of_item;
;     if (!have_next) break;
	ds_bpermute_b32 v96, v168, v113
	s_lshl_b32 s0, s65, s40
	s_lshl_b32 s1, s66, 7
	s_add_i32 s0, s0, s1
	s_waitcnt vmcnt(3)
	v_lshlrev_b32_e32 v100, 16, v160
	s_waitcnt lgkmcnt(0)
	v_add_f32_e32 v98, v113, v96
	ds_bpermute_b32 v99, v169, v98
	v_add_u32_e32 v96, s0, v145
	v_ashrrev_i32_e32 v97, 31, v96
	v_lshlrev_b64 v[96:97], 11, v[96:97]
	v_and_b32_e32 v101, 0xffff0000, v160
	s_waitcnt lgkmcnt(0)
	v_add_f32_e32 v98, v98, v99
	v_rcp_f32_e32 v98, v98
	s_lshl_b32 s20, s63, 8
	v_lshl_add_u64 v[96:97], s[6:7], 0, v[96:97]
	v_lshl_add_u64 v[96:97], v[96:97], 0, s[20:21]
	v_pk_mul_f32 v[102:103], v[92:93], v[98:99] op_sel_hi:[1,0]
	v_pk_mul_f32 v[104:105], v[94:95], v[98:99] op_sel_hi:[1,0]
	v_pk_mul_f32 v[100:101], v[102:103], v[100:101]
	v_lshlrev_b32_e32 v102, 16, v161
	v_and_b32_e32 v103, 0xffff0000, v161
	v_mov_b32_e32 v159, v187
	v_pk_mul_f32 v[102:103], v[104:105], v[102:103]
	v_lshl_add_u64 v[96:97], v[96:97], 0, v[158:159]
	v_cvt_pk_bf16_f32 v100, v100, v101
	v_cvt_pk_bf16_f32 v101, v102, v103
	global_store_dwordx2 v[96:97], v[100:101], off
	s_waitcnt vmcnt(4)
	v_lshlrev_b32_e32 v100, 16, v162
	v_and_b32_e32 v101, 0xffff0000, v162
	v_pk_mul_f32 v[102:103], v[88:89], v[98:99] op_sel_hi:[1,0]
	v_pk_mul_f32 v[104:105], v[90:91], v[98:99] op_sel_hi:[1,0]
	v_pk_mul_f32 v[100:101], v[102:103], v[100:101]
	v_lshlrev_b32_e32 v102, 16, v163
	v_and_b32_e32 v103, 0xffff0000, v163
	v_pk_mul_f32 v[102:103], v[104:105], v[102:103]
	v_cvt_pk_bf16_f32 v100, v100, v101
	v_cvt_pk_bf16_f32 v101, v102, v103
	global_store_dwordx2 v[96:97], v[100:101], off offset:32
	s_waitcnt vmcnt(4)
	v_lshlrev_b32_e32 v100, 16, v154
	v_and_b32_e32 v101, 0xffff0000, v154
	v_pk_mul_f32 v[102:103], v[84:85], v[98:99] op_sel_hi:[1,0]
	v_pk_mul_f32 v[104:105], v[86:87], v[98:99] op_sel_hi:[1,0]
	v_pk_mul_f32 v[100:101], v[102:103], v[100:101]
	v_lshlrev_b32_e32 v102, 16, v155
	v_and_b32_e32 v103, 0xffff0000, v155
	v_pk_mul_f32 v[102:103], v[104:105], v[102:103]
	v_cvt_pk_bf16_f32 v100, v100, v101
	v_cvt_pk_bf16_f32 v101, v102, v103
	global_store_dwordx2 v[96:97], v[100:101], off offset:64
	s_waitcnt vmcnt(5)
	v_lshlrev_b32_e32 v100, 16, v156
	v_and_b32_e32 v101, 0xffff0000, v156
	v_pk_mul_f32 v[102:103], v[80:81], v[98:99] op_sel_hi:[1,0]
	v_pk_mul_f32 v[104:105], v[82:83], v[98:99] op_sel_hi:[1,0]
	v_pk_mul_f32 v[100:101], v[102:103], v[100:101]
	v_lshlrev_b32_e32 v102, 16, v157
	v_and_b32_e32 v103, 0xffff0000, v157
	v_pk_mul_f32 v[102:103], v[104:105], v[102:103]
	v_cvt_pk_bf16_f32 v100, v100, v101
	v_cvt_pk_bf16_f32 v101, v102, v103
	global_store_dwordx2 v[96:97], v[100:101], off offset:96
	s_waitcnt vmcnt(5)
	v_lshlrev_b32_e32 v100, 16, v150
	v_and_b32_e32 v101, 0xffff0000, v150
	v_pk_mul_f32 v[102:103], v[76:77], v[98:99] op_sel_hi:[1,0]
	v_pk_mul_f32 v[104:105], v[78:79], v[98:99] op_sel_hi:[1,0]
	v_pk_mul_f32 v[100:101], v[102:103], v[100:101]
	v_lshlrev_b32_e32 v102, 16, v151
	v_and_b32_e32 v103, 0xffff0000, v151
	v_pk_mul_f32 v[102:103], v[104:105], v[102:103]
	v_cvt_pk_bf16_f32 v100, v100, v101
	v_cvt_pk_bf16_f32 v101, v102, v103
	global_store_dwordx2 v[96:97], v[100:101], off offset:128
	s_waitcnt vmcnt(6)
	v_lshlrev_b32_e32 v100, 16, v152
	v_and_b32_e32 v101, 0xffff0000, v152
	v_pk_mul_f32 v[102:103], v[72:73], v[98:99] op_sel_hi:[1,0]
	v_pk_mul_f32 v[104:105], v[74:75], v[98:99] op_sel_hi:[1,0]
	v_pk_mul_f32 v[100:101], v[102:103], v[100:101]
	v_lshlrev_b32_e32 v102, 16, v153
	v_and_b32_e32 v103, 0xffff0000, v153
	v_pk_mul_f32 v[102:103], v[104:105], v[102:103]
	v_cvt_pk_bf16_f32 v100, v100, v101
	v_cvt_pk_bf16_f32 v101, v102, v103
	global_store_dwordx2 v[96:97], v[100:101], off offset:160
	s_waitcnt vmcnt(6)
	v_lshlrev_b32_e32 v100, 16, v146
	v_and_b32_e32 v101, 0xffff0000, v146
	v_pk_mul_f32 v[102:103], v[68:69], v[98:99] op_sel_hi:[1,0]
	v_pk_mul_f32 v[104:105], v[70:71], v[98:99] op_sel_hi:[1,0]
	v_pk_mul_f32 v[100:101], v[102:103], v[100:101]
	v_lshlrev_b32_e32 v102, 16, v147
	v_and_b32_e32 v103, 0xffff0000, v147
	v_pk_mul_f32 v[102:103], v[104:105], v[102:103]
	v_cvt_pk_bf16_f32 v100, v100, v101
	v_cvt_pk_bf16_f32 v101, v102, v103
	global_store_dwordx2 v[96:97], v[100:101], off offset:192
	s_waitcnt vmcnt(7)
	v_lshlrev_b32_e32 v100, 16, v148
	v_and_b32_e32 v101, 0xffff0000, v148
	v_pk_mul_f32 v[102:103], v[64:65], v[98:99] op_sel_hi:[1,0]
	v_pk_mul_f32 v[98:99], v[66:67], v[98:99] op_sel_hi:[1,0]
	v_pk_mul_f32 v[100:101], v[102:103], v[100:101]
	v_lshlrev_b32_e32 v102, 16, v149
	v_and_b32_e32 v103, 0xffff0000, v149
	v_pk_mul_f32 v[98:99], v[98:99], v[102:103]
	v_cvt_pk_bf16_f32 v100, v100, v101
	v_cvt_pk_bf16_f32 v101, v98, v99
	global_store_dwordx2 v[96:97], v[100:101], off offset:224
	s_xor_b64 s[4:5], s[12:13], -1
	s_branch .Lattn_top_nowait
